# wave priority 2 during the 128x128 in-proj tile (phase B, workgroups 256..511), reset after its store loop
# speedup vs baseline: 1.0119x; 1.0119x over previous
; DI char* opq(char* q) { size_t z = 0; asm volatile("" : "+s"(z)); return q + z; }
; DI int tidx() { int t = threadIdx.x; asm volatile("" : "+v"(t)); return t; }
; #define GLOAD(dst, kt_) _Pragma("unroll") for (int i = 0; i < NCH; ++i) { dst[i] = (i < NCHW) ? ldw(i, tid >> 3, (kt_) * 64 + (tid & 7) * 8) : ldx(i - NCHW, tid >> 3, (kt_) * 64 + (tid & 7) * 8); }
; #define LSTORE(src, base) _Pragma("unroll") for (int i = 0; i < NCH; ++i) { const int c = tid + 256 * i; *(u32x4*)((base) + (c >> 3) * 144 + (c & 7) * 16) = src[i]; }
; template <int WGN, int INS, int IMS, bool DB, class LdW, class LdX>
; DI void gemm_core(f32x16 (&acc)[INS][IMS], const int KT, LdW ldw, LdX ldx, char* lds, const int tid) {
;     ...
;   if (DB) {
;     u32x4 preA[NCH], preB[NCH];
;     GLOAD(preA, 0)
;     GLOAD(preB, 1)
;     __syncthreads();
;     LSTORE(preA, lds)
;     __syncthreads();
; template <int NTW>
; DI void inproj_tile(const Params& p, int l, int mt, int ntile, char* lds) {
;   char* const ws_ = opq(p.ws);
;   const u16* W = (const u16*)(ws_ + OFF_WIN) + ((size_t)l * NP + ntile * 64 * NTW) * 1024;
;   const u16* X = (const u16*)(ws_ + OFF_XB) + (size_t)mt * 128 * 1024;
;   f32x16 acc[NTW][2];
;   const int tid = tidx();
;   gemm_core<2, NTW, 2, (NTW == 2)>(acc, 16, [&](int i, int r0, int k) -> u32x4 { return *(const u32x4*)((W + i * 32768) + (unsigned)(r0 * 1024 + k)); },
;                [&](int i, int r0, int k) -> u32x4 { return *(const u32x4*)((X + i * 32768) + (unsigned)(r0 * 1024 + k)); }, lds, tid);
.Lb_items:
	s_cmp_gt_i32 s36, 63
	s_mov_b64 s[0:1], -1
	s_cbranch_scc0 .LBB0_285
	s_cmpk_lt_u32 s36, 0x100
	s_cbranch_scc1 .LBB0_225
	s_setprio 2
	s_and_b32 s14, s36, 0x7fffff80
	s_mov_b64 s[0:1], 0
	s_add_u32 s12, s90, s0
	s_addc_u32 s13, s91, s1
	s_addk_i32 s14, 0xb00
	s_add_i32 s0, s14, s28
	s_mov_b32 s1, s81
	s_lshl_b64 s[0:1], s[0:1], 11
	s_add_u32 s4, s12, s0
	s_addc_u32 s5, s13, s1
	s_add_u32 s10, s12, s26
	s_addc_u32 s11, s13, 0
	v_mov_b32_e32 v86, v176
	s_add_u32 s0, s4, 0x10000
	v_lshlrev_b32_e32 v0, 3, v86
	v_and_b32_e32 v0, 56, v0
	v_lshlrev_b32_e32 v1, 7, v86
	s_addc_u32 s1, s5, 0
	v_and_or_b32 v178, v1, s70, v0
	s_add_u32 s2, s4, 0x20000
	v_lshlrev_b64 v[28:29], 1, v[178:179]
	s_addc_u32 s3, s5, 0
	v_lshl_add_u64 v[72:73], s[4:5], 0, v[28:29]
	v_lshl_add_u64 v[4:5], s[0:1], 0, v[28:29]
	v_lshl_add_u64 v[8:9], s[2:3], 0, v[28:29]
	global_load_dwordx4 v[0:3], v[72:73], off
	s_nop 0
	global_load_dwordx4 v[4:7], v[4:5], off
	s_nop 0
	global_load_dwordx4 v[8:11], v[8:9], off
	s_add_u32 s4, s4, 0x30000
	s_addc_u32 s5, s5, 0
	s_add_u32 s6, s10, 0x2a50000
	s_addc_u32 s7, s11, 0
	s_add_u32 s8, s10, 0x2a60000
	s_addc_u32 s9, s11, 0
	v_lshl_add_u64 v[32:33], s[10:11], 0, v[28:29]
	s_add_u32 s10, s10, 0x2a70000
	v_add_co_u32_e32 v16, vcc, s74, v32
	s_addc_u32 s11, s11, 0
	v_lshl_add_u64 v[12:13], s[4:5], 0, v[28:29]
	v_addc_co_u32_e32 v17, vcc, 0, v33, vcc
	v_lshl_add_u64 v[20:21], s[6:7], 0, v[28:29]
	v_lshl_add_u64 v[24:25], s[8:9], 0, v[28:29]
	v_lshl_add_u64 v[28:29], s[10:11], 0, v[28:29]
	global_load_dwordx4 v[12:15], v[12:13], off
	v_ashrrev_i32_e32 v34, 1, v86
	global_load_dwordx4 v[16:19], v[16:17], off
	v_lshrrev_b32_e32 v36, 1, v86
	global_load_dwordx4 v[20:23], v[20:21], off
	v_lshlrev_b32_e32 v37, 4, v86
	global_load_dwordx4 v[24:27], v[24:25], off
	v_add_u32_e32 v39, 0x100, v86
	global_load_dwordx4 v[28:31], v[28:29], off
	v_add_u32_e32 v40, 0x200, v86
	v_and_b32_e32 v88, 0xffffffc0, v34
	v_lshrrev_b32_e32 v87, 3, v86
	v_and_b32_e32 v36, 16, v36
	v_and_b32_e32 v38, 0x70, v37
	v_lshrrev_b32_e32 v34, 3, v39
	v_lshrrev_b32_e32 v37, 3, v40
	v_and_or_b32 v39, v86, 31, v88
	v_mov_b32_e32 v35, v179
	v_mad_u64_u32 v[66:67], s[16:17], v87, s71, v[38:39]
	v_mad_u64_u32 v[68:69], s[16:17], v34, s71, v[38:39]
	v_mad_u64_u32 v[70:71], s[16:17], v37, s71, v[38:39]
	v_mad_u64_u32 v[64:65], s[16:17], v39, s71, v[36:37]
	v_or_b32_e32 v34, 64, v178
	v_lshlrev_b64 v[34:35], 1, v[34:35]
	s_mov_b64 s[16:17], 0x2a40000
	v_lshl_add_u64 v[84:85], v[32:33], 0, s[16:17]
	v_lshl_add_u64 v[32:33], s[0:1], 0, v[34:35]
	global_load_dwordx4 v[90:93], v[72:73], off offset:128
	v_lshl_add_u64 v[40:41], s[2:3], 0, v[34:35]
	global_load_dwordx4 v[94:97], v[32:33], off
	global_load_dwordx4 v[98:101], v[40:41], off
	v_lshl_add_u64 v[32:33], s[4:5], 0, v[34:35]
	global_load_dwordx4 v[102:105], v[84:85], off offset:128
	v_lshl_add_u64 v[40:41], s[6:7], 0, v[34:35]
	global_load_dwordx4 v[106:109], v[32:33], off
	global_load_dwordx4 v[110:113], v[40:41], off
	v_lshl_add_u64 v[32:33], s[8:9], 0, v[34:35]
	v_lshl_add_u64 v[34:35], s[10:11], 0, v[34:35]
	global_load_dwordx4 v[114:117], v[32:33], off
	global_load_dwordx4 v[118:121], v[34:35], off
	s_barrier
	v_and_b32_e32 v65, 0x5f, v86
	v_mad_u32_u24 v67, v65, s71, v36
	s_waitcnt vmcnt(15)
	ds_write_b128 v66, v[0:3]
	s_waitcnt vmcnt(14)
	ds_write_b128 v68, v[4:7]
	s_waitcnt vmcnt(13)
	ds_write_b128 v70, v[8:11]
	v_add_u32_e32 v0, 0x300, v86
	v_lshrrev_b32_e32 v0, 3, v0
	v_mad_u64_u32 v[74:75], s[16:17], v0, s71, v[38:39]
	v_add_u32_e32 v0, 0x400, v86
	v_lshrrev_b32_e32 v0, 3, v0
	v_mad_u64_u32 v[76:77], s[16:17], v0, s71, v[38:39]
	v_add_u32_e32 v0, 0x500, v86
	v_lshrrev_b32_e32 v0, 3, v0
	v_mad_u64_u32 v[78:79], s[16:17], v0, s71, v[38:39]
	v_add_u32_e32 v0, 0x600, v86
	v_lshrrev_b32_e32 v0, 3, v0
	v_mad_u64_u32 v[80:81], s[16:17], v0, s71, v[38:39]
	v_add_u32_e32 v0, 0x700, v86
	v_lshrrev_b32_e32 v0, 3, v0
	v_mad_u64_u32 v[82:83], s[16:17], v0, s71, v[38:39]
	s_waitcnt vmcnt(12)
	ds_write_b128 v74, v[12:15]
	s_waitcnt vmcnt(11)
	ds_write_b128 v76, v[16:19]
	s_waitcnt vmcnt(10)
	ds_write_b128 v78, v[20:23]
	s_waitcnt vmcnt(9)
	ds_write_b128 v80, v[24:27]
	s_waitcnt vmcnt(8)
	ds_write_b128 v82, v[28:31]
	s_waitcnt lgkmcnt(0)
	s_barrier
; #define GLOAD(dst, kt_) _Pragma("unroll") for (int i = 0; i < NCH; ++i) { dst[i] = (i < NCHW) ? ldw(i, tid >> 3, (kt_) * 64 + (tid & 7) * 8) : ldx(i - NCHW, tid >> 3, (kt_) * 64 + (tid & 7) * 8); }
; #define LSTORE(src, base) _Pragma("unroll") for (int i = 0; i < NCH; ++i) { const int c = tid + 256 * i; *(u32x4*)((base) + (c >> 3) * 144 + (c & 7) * 16) = src[i]; }
; template <int WGN, int INS, int IMS, bool DB, class LdW, class LdX>
; DI void gemm_core(f32x16 (&acc)[INS][IMS], const int KT, LdW ldw, LdX ldx, char* lds, const int tid) {
;     ...
;     for (int kt = 0; kt < KT; kt += 2) {
;       if (kt + 2 < KT) { GLOAD(preA, kt + 2) }
;       COMPUTE_PIPE(lds)
;       LSTORE(preB, lds + BUFB)
;       __syncthreads();
;       if (kt + 3 < KT) { GLOAD(preB, kt + 3) }
;       COMPUTE_PIPE(lds + BUFB)
;       if (kt + 2 < KT) { LSTORE(preA, lds) }
;       __syncthreads();
;     }
	ds_read_b128 v[0:3], v64
	ds_read_b128 v[4:7], v67 offset:18432
	ds_read_b128 v[122:125], v64 offset:32
	ds_read_b128 v[126:129], v67 offset:18464
	ds_read_b128 v[8:11], v64 offset:4608
	ds_read_b128 v[130:133], v64 offset:4640
	s_waitcnt lgkmcnt(4)
	v_mfma_f32_32x32x16_bf16 v[48:63], v[0:3], v[4:7], 0
	s_waitcnt lgkmcnt(1)
	v_mfma_f32_32x32x16_bf16 v[32:47], v[8:11], v[4:7], 0
	ds_read_b128 v[4:7], v67 offset:23040
	ds_read_b128 v[134:137], v67 offset:23072
	s_waitcnt lgkmcnt(1)
	v_mfma_f32_32x32x16_bf16 v[16:31], v[0:3], v[4:7], 0
	v_mfma_f32_32x32x16_bf16 v[0:15], v[8:11], v[4:7], 0
	v_mfma_f32_32x32x16_bf16 v[48:63], v[122:125], v[126:129], v[48:63]
	v_mfma_f32_32x32x16_bf16 v[32:47], v[130:133], v[126:129], v[32:47]
	s_waitcnt lgkmcnt(0)
	v_mfma_f32_32x32x16_bf16 v[16:31], v[122:125], v[134:137], v[16:31]
	v_mfma_f32_32x32x16_bf16 v[0:15], v[130:133], v[134:137], v[0:15]
	ds_read_b128 v[122:125], v64 offset:64
	ds_read_b128 v[126:129], v67 offset:18496
	ds_read_b128 v[130:133], v64 offset:96
	ds_read_b128 v[134:137], v67 offset:18528
	ds_read_b128 v[138:141], v64 offset:4672
	ds_read_b128 v[142:145], v64 offset:4704
	s_waitcnt lgkmcnt(4)
	v_mfma_f32_32x32x16_bf16 v[48:63], v[122:125], v[126:129], v[48:63]
	s_waitcnt lgkmcnt(1)
	v_mfma_f32_32x32x16_bf16 v[32:47], v[138:141], v[126:129], v[32:47]
	ds_read_b128 v[126:129], v67 offset:23104
	ds_read_b128 v[146:149], v67 offset:23136
	s_waitcnt lgkmcnt(1)
	v_mfma_f32_32x32x16_bf16 v[16:31], v[122:125], v[126:129], v[16:31]
	v_or_b32_e32 v122, 0x80, v178
	v_mov_b32_e32 v123, v179
	v_lshlrev_b64 v[154:155], 1, v[122:123]
	v_lshl_add_u64 v[122:123], s[0:1], 0, v[154:155]
	v_lshl_add_u64 v[150:151], s[4:5], 0, v[154:155]
	v_lshl_add_u64 v[152:153], s[6:7], 0, v[154:155]
	v_lshl_add_u64 v[156:157], s[8:9], 0, v[154:155]
	v_mfma_f32_32x32x16_bf16 v[0:15], v[138:141], v[126:129], v[0:15]
	v_lshl_add_u64 v[126:127], s[2:3], 0, v[154:155]
	v_lshl_add_u64 v[158:159], s[10:11], 0, v[154:155]
	global_load_dwordx4 v[122:125], v[122:123], off
	s_nop 0
	global_load_dwordx4 v[126:129], v[126:127], off
	v_mfma_f32_32x32x16_bf16 v[48:63], v[130:133], v[134:137], v[48:63]
	v_mfma_f32_32x32x16_bf16 v[32:47], v[142:145], v[134:137], v[32:47]
	global_load_dwordx4 v[134:137], v[72:73], off offset:256
	global_load_dwordx4 v[138:141], v[84:85], off offset:256
	s_waitcnt lgkmcnt(0)
	v_mfma_f32_32x32x16_bf16 v[16:31], v[130:133], v[146:149], v[16:31]
	global_load_dwordx4 v[130:133], v[150:151], off
	s_nop 0
	global_load_dwordx4 v[150:153], v[152:153], off
	s_nop 0
	global_load_dwordx4 v[154:157], v[156:157], off
	s_nop 0
	global_load_dwordx4 v[158:161], v[158:159], off
	s_waitcnt vmcnt(15)
	ds_write_b128 v66, v[90:93] offset:36864
	s_waitcnt vmcnt(14)
	ds_write_b128 v68, v[94:97] offset:36864
	s_waitcnt vmcnt(13)
	ds_write_b128 v70, v[98:101] offset:36864
	s_waitcnt vmcnt(11)
	ds_write_b128 v74, v[106:109] offset:36864
	ds_write_b128 v76, v[102:105] offset:36864
	s_waitcnt vmcnt(10)
	ds_write_b128 v78, v[110:113] offset:36864
	s_waitcnt vmcnt(9)
	ds_write_b128 v80, v[114:117] offset:36864
	s_waitcnt vmcnt(8)
	ds_write_b128 v82, v[118:121] offset:36864
	s_waitcnt lgkmcnt(0)
	s_barrier
	ds_read_b128 v[90:93], v64 offset:36864
	ds_read_b128 v[94:97], v67 offset:55296
	ds_read_b128 v[98:101], v64 offset:36896
	ds_read_b128 v[102:105], v67 offset:55328
	v_mfma_f32_32x32x16_bf16 v[0:15], v[142:145], v[146:149], v[0:15]
	ds_read_b128 v[106:109], v64 offset:41472
	ds_read_b128 v[110:113], v64 offset:41504
	s_waitcnt lgkmcnt(4)
	v_mfma_f32_32x32x16_bf16 v[48:63], v[90:93], v[94:97], v[48:63]
	s_waitcnt lgkmcnt(1)
	v_mfma_f32_32x32x16_bf16 v[32:47], v[106:109], v[94:97], v[32:47]
	ds_read_b128 v[94:97], v67 offset:59904
	ds_read_b128 v[114:117], v67 offset:59936
	s_waitcnt lgkmcnt(1)
	v_mfma_f32_32x32x16_bf16 v[16:31], v[90:93], v[94:97], v[16:31]
	v_mfma_f32_32x32x16_bf16 v[0:15], v[106:109], v[94:97], v[0:15]
	v_mfma_f32_32x32x16_bf16 v[48:63], v[98:101], v[102:105], v[48:63]
	v_mfma_f32_32x32x16_bf16 v[32:47], v[110:113], v[102:105], v[32:47]
	s_waitcnt lgkmcnt(0)
	v_mfma_f32_32x32x16_bf16 v[16:31], v[98:101], v[114:117], v[16:31]
	ds_read_b128 v[90:93], v64 offset:36928
	ds_read_b128 v[94:97], v67 offset:55360
	ds_read_b128 v[98:101], v64 offset:36960
	ds_read_b128 v[102:105], v67 offset:55392
	v_mfma_f32_32x32x16_bf16 v[0:15], v[110:113], v[114:117], v[0:15]
	ds_read_b128 v[106:109], v64 offset:41536
	ds_read_b128 v[110:113], v64 offset:41568
	s_waitcnt lgkmcnt(4)
	v_mfma_f32_32x32x16_bf16 v[48:63], v[90:93], v[94:97], v[48:63]
	s_waitcnt lgkmcnt(1)
	v_mfma_f32_32x32x16_bf16 v[32:47], v[106:109], v[94:97], v[32:47]
	ds_read_b128 v[94:97], v67 offset:59968
	ds_read_b128 v[114:117], v67 offset:60000
	s_waitcnt lgkmcnt(1)
	v_mfma_f32_32x32x16_bf16 v[16:31], v[90:93], v[94:97], v[16:31]
	v_or_b32_e32 v90, 0xc0, v178
	v_mov_b32_e32 v91, v179
	v_lshlrev_b64 v[142:143], 1, v[90:91]
	v_lshl_add_u64 v[90:91], s[0:1], 0, v[142:143]
	v_lshl_add_u64 v[118:119], s[4:5], 0, v[142:143]
	v_lshl_add_u64 v[120:121], s[6:7], 0, v[142:143]
	v_lshl_add_u64 v[144:145], s[8:9], 0, v[142:143]
	v_mfma_f32_32x32x16_bf16 v[0:15], v[106:109], v[94:97], v[0:15]
	v_lshl_add_u64 v[94:95], s[2:3], 0, v[142:143]
	v_lshl_add_u64 v[146:147], s[10:11], 0, v[142:143]
	global_load_dwordx4 v[90:93], v[90:91], off
	s_nop 0
	global_load_dwordx4 v[94:97], v[94:95], off
	v_mfma_f32_32x32x16_bf16 v[48:63], v[98:101], v[102:105], v[48:63]
	v_mfma_f32_32x32x16_bf16 v[32:47], v[110:113], v[102:105], v[32:47]
	global_load_dwordx4 v[102:105], v[72:73], off offset:384
	global_load_dwordx4 v[106:109], v[84:85], off offset:384
	s_waitcnt lgkmcnt(0)
	v_mfma_f32_32x32x16_bf16 v[16:31], v[98:101], v[114:117], v[16:31]
	global_load_dwordx4 v[98:101], v[118:119], off
	s_nop 0
	global_load_dwordx4 v[118:121], v[120:121], off
	s_nop 0
	global_load_dwordx4 v[142:145], v[144:145], off
	s_nop 0
	global_load_dwordx4 v[146:149], v[146:147], off
	s_waitcnt vmcnt(13)
	ds_write_b128 v66, v[134:137]
	ds_write_b128 v68, v[122:125]
	ds_write_b128 v70, v[126:129]
	s_waitcnt vmcnt(11)
	ds_write_b128 v74, v[130:133]
	ds_write_b128 v76, v[138:141]
	s_waitcnt vmcnt(10)
	ds_write_b128 v78, v[150:153]
	s_waitcnt vmcnt(9)
	ds_write_b128 v80, v[154:157]
	s_waitcnt vmcnt(8)
	ds_write_b128 v82, v[158:161]
	s_waitcnt lgkmcnt(0)
	s_barrier
; #define GLOAD(dst, kt_) _Pragma("unroll") for (int i = 0; i < NCH; ++i) { dst[i] = (i < NCHW) ? ldw(i, tid >> 3, (kt_) * 64 + (tid & 7) * 8) : ldx(i - NCHW, tid >> 3, (kt_) * 64 + (tid & 7) * 8); }
; #define LSTORE(src, base) _Pragma("unroll") for (int i = 0; i < NCH; ++i) { const int c = tid + 256 * i; *(u32x4*)((base) + (c >> 3) * 144 + (c & 7) * 16) = src[i]; }
; template <int WGN, int INS, int IMS, bool DB, class LdW, class LdX>
; DI void gemm_core(f32x16 (&acc)[INS][IMS], const int KT, LdW ldw, LdX ldx, char* lds, const int tid) {
;     ...
;     for (int kt = 0; kt < KT; kt += 2) {
;       if (kt + 2 < KT) { GLOAD(preA, kt + 2) }
;       COMPUTE_PIPE(lds)
;       LSTORE(preB, lds + BUFB)
;       __syncthreads();
;       if (kt + 3 < KT) { GLOAD(preB, kt + 3) }
;       COMPUTE_PIPE(lds + BUFB)
;       if (kt + 2 < KT) { LSTORE(preA, lds) }
;       __syncthreads();
;     }
	v_mfma_f32_32x32x16_bf16 v[0:15], v[110:113], v[114:117], v[0:15]
	ds_read_b128 v[110:113], v64
	ds_read_b128 v[114:117], v67 offset:18432
	ds_read_b128 v[122:125], v64 offset:32
	ds_read_b128 v[126:129], v67 offset:18464
	ds_read_b128 v[130:133], v64 offset:4608
	ds_read_b128 v[134:137], v64 offset:4640
	s_waitcnt lgkmcnt(4)
	v_mfma_f32_32x32x16_bf16 v[48:63], v[110:113], v[114:117], v[48:63]
	s_waitcnt lgkmcnt(1)
	v_mfma_f32_32x32x16_bf16 v[32:47], v[130:133], v[114:117], v[32:47]
	ds_read_b128 v[114:117], v67 offset:23040
	ds_read_b128 v[138:141], v67 offset:23072
	s_waitcnt lgkmcnt(1)
	v_mfma_f32_32x32x16_bf16 v[16:31], v[110:113], v[114:117], v[16:31]
	v_mfma_f32_32x32x16_bf16 v[0:15], v[130:133], v[114:117], v[0:15]
	v_mfma_f32_32x32x16_bf16 v[48:63], v[122:125], v[126:129], v[48:63]
	v_mfma_f32_32x32x16_bf16 v[32:47], v[134:137], v[126:129], v[32:47]
	s_waitcnt lgkmcnt(0)
	v_mfma_f32_32x32x16_bf16 v[16:31], v[122:125], v[138:141], v[16:31]
	ds_read_b128 v[110:113], v64 offset:64
	ds_read_b128 v[114:117], v67 offset:18496
	ds_read_b128 v[122:125], v64 offset:96
	ds_read_b128 v[126:129], v67 offset:18528
	v_mfma_f32_32x32x16_bf16 v[0:15], v[134:137], v[138:141], v[0:15]
	ds_read_b128 v[130:133], v64 offset:4672
	ds_read_b128 v[134:137], v64 offset:4704
	s_waitcnt lgkmcnt(4)
	v_mfma_f32_32x32x16_bf16 v[48:63], v[110:113], v[114:117], v[48:63]
	s_waitcnt lgkmcnt(1)
	v_mfma_f32_32x32x16_bf16 v[32:47], v[130:133], v[114:117], v[32:47]
	ds_read_b128 v[114:117], v67 offset:23104
	ds_read_b128 v[138:141], v67 offset:23136
	s_waitcnt lgkmcnt(1)
	v_mfma_f32_32x32x16_bf16 v[16:31], v[110:113], v[114:117], v[16:31]
	v_or_b32_e32 v110, 0x100, v178
	v_mov_b32_e32 v111, v179
	v_lshlrev_b64 v[154:155], 1, v[110:111]
	v_lshl_add_u64 v[110:111], s[0:1], 0, v[154:155]
	v_lshl_add_u64 v[150:151], s[4:5], 0, v[154:155]
	v_lshl_add_u64 v[152:153], s[6:7], 0, v[154:155]
	v_lshl_add_u64 v[156:157], s[8:9], 0, v[154:155]
	v_mfma_f32_32x32x16_bf16 v[0:15], v[130:133], v[114:117], v[0:15]
	v_lshl_add_u64 v[114:115], s[2:3], 0, v[154:155]
	v_lshl_add_u64 v[158:159], s[10:11], 0, v[154:155]
	global_load_dwordx4 v[110:113], v[110:111], off
	s_nop 0
	global_load_dwordx4 v[114:117], v[114:115], off
	v_mfma_f32_32x32x16_bf16 v[48:63], v[122:125], v[126:129], v[48:63]
	v_mfma_f32_32x32x16_bf16 v[32:47], v[134:137], v[126:129], v[32:47]
	global_load_dwordx4 v[126:129], v[72:73], off offset:512
	global_load_dwordx4 v[130:133], v[84:85], off offset:512
	s_waitcnt lgkmcnt(0)
	v_mfma_f32_32x32x16_bf16 v[16:31], v[122:125], v[138:141], v[16:31]
	global_load_dwordx4 v[122:125], v[150:151], off
	s_nop 0
	global_load_dwordx4 v[150:153], v[152:153], off
	s_nop 0
	global_load_dwordx4 v[154:157], v[156:157], off
	s_nop 0
	global_load_dwordx4 v[158:161], v[158:159], off
	s_waitcnt vmcnt(13)
	ds_write_b128 v66, v[102:105] offset:36864
	ds_write_b128 v68, v[90:93] offset:36864
	ds_write_b128 v70, v[94:97] offset:36864
	s_waitcnt vmcnt(11)
	ds_write_b128 v74, v[98:101] offset:36864
	ds_write_b128 v76, v[106:109] offset:36864
	s_waitcnt vmcnt(10)
	ds_write_b128 v78, v[118:121] offset:36864
	s_waitcnt vmcnt(9)
	ds_write_b128 v80, v[142:145] offset:36864
	s_waitcnt vmcnt(8)
	ds_write_b128 v82, v[146:149] offset:36864
	s_waitcnt lgkmcnt(0)
	s_barrier
	ds_read_b128 v[90:93], v64 offset:36864
	ds_read_b128 v[94:97], v67 offset:55296
	ds_read_b128 v[98:101], v64 offset:36896
	ds_read_b128 v[102:105], v67 offset:55328
	v_mfma_f32_32x32x16_bf16 v[0:15], v[134:137], v[138:141], v[0:15]
	ds_read_b128 v[106:109], v64 offset:41472
	ds_read_b128 v[118:121], v64 offset:41504
	s_waitcnt lgkmcnt(4)
	v_mfma_f32_32x32x16_bf16 v[48:63], v[90:93], v[94:97], v[48:63]
	s_waitcnt lgkmcnt(1)
	v_mfma_f32_32x32x16_bf16 v[32:47], v[106:109], v[94:97], v[32:47]
	ds_read_b128 v[94:97], v67 offset:59904
	ds_read_b128 v[134:137], v67 offset:59936
	s_waitcnt lgkmcnt(1)
	v_mfma_f32_32x32x16_bf16 v[16:31], v[90:93], v[94:97], v[16:31]
	v_mfma_f32_32x32x16_bf16 v[0:15], v[106:109], v[94:97], v[0:15]
	v_mfma_f32_32x32x16_bf16 v[48:63], v[98:101], v[102:105], v[48:63]
	v_mfma_f32_32x32x16_bf16 v[32:47], v[118:121], v[102:105], v[32:47]
	s_waitcnt lgkmcnt(0)
	v_mfma_f32_32x32x16_bf16 v[16:31], v[98:101], v[134:137], v[16:31]
	ds_read_b128 v[90:93], v64 offset:36928
	ds_read_b128 v[94:97], v67 offset:55360
	ds_read_b128 v[98:101], v64 offset:36960
	ds_read_b128 v[102:105], v67 offset:55392
	v_mfma_f32_32x32x16_bf16 v[0:15], v[118:121], v[134:137], v[0:15]
	ds_read_b128 v[106:109], v64 offset:41536
	ds_read_b128 v[118:121], v64 offset:41568
	s_waitcnt lgkmcnt(4)
	v_mfma_f32_32x32x16_bf16 v[48:63], v[90:93], v[94:97], v[48:63]
	s_waitcnt lgkmcnt(1)
	v_mfma_f32_32x32x16_bf16 v[32:47], v[106:109], v[94:97], v[32:47]
	ds_read_b128 v[94:97], v67 offset:59968
	ds_read_b128 v[134:137], v67 offset:60000
	s_waitcnt lgkmcnt(1)
	v_mfma_f32_32x32x16_bf16 v[16:31], v[90:93], v[94:97], v[16:31]
	v_or_b32_e32 v90, 0x140, v178
	v_mov_b32_e32 v91, v179
	v_lshlrev_b64 v[142:143], 1, v[90:91]
	v_lshl_add_u64 v[90:91], s[0:1], 0, v[142:143]
	v_lshl_add_u64 v[138:139], s[4:5], 0, v[142:143]
	v_lshl_add_u64 v[140:141], s[6:7], 0, v[142:143]
	v_lshl_add_u64 v[144:145], s[8:9], 0, v[142:143]
	v_mfma_f32_32x32x16_bf16 v[0:15], v[106:109], v[94:97], v[0:15]
	v_lshl_add_u64 v[94:95], s[2:3], 0, v[142:143]
	v_lshl_add_u64 v[146:147], s[10:11], 0, v[142:143]
	global_load_dwordx4 v[90:93], v[90:91], off
	s_nop 0
	global_load_dwordx4 v[94:97], v[94:95], off
	v_mfma_f32_32x32x16_bf16 v[48:63], v[98:101], v[102:105], v[48:63]
	v_mfma_f32_32x32x16_bf16 v[32:47], v[118:121], v[102:105], v[32:47]
	global_load_dwordx4 v[102:105], v[72:73], off offset:640
	global_load_dwordx4 v[106:109], v[84:85], off offset:640
	s_waitcnt lgkmcnt(0)
	v_mfma_f32_32x32x16_bf16 v[16:31], v[98:101], v[134:137], v[16:31]
	global_load_dwordx4 v[98:101], v[138:139], off
	s_nop 0
	global_load_dwordx4 v[138:141], v[140:141], off
	s_nop 0
	global_load_dwordx4 v[142:145], v[144:145], off
	s_nop 0
	global_load_dwordx4 v[146:149], v[146:147], off
	s_waitcnt vmcnt(13)
	ds_write_b128 v66, v[126:129]
	ds_write_b128 v68, v[110:113]
	ds_write_b128 v70, v[114:117]
	s_waitcnt vmcnt(11)
	ds_write_b128 v74, v[122:125]
	ds_write_b128 v76, v[130:133]
	s_waitcnt vmcnt(10)
	ds_write_b128 v78, v[150:153]
	s_waitcnt vmcnt(9)
	ds_write_b128 v80, v[154:157]
	s_waitcnt vmcnt(8)
	ds_write_b128 v82, v[158:161]
	s_waitcnt lgkmcnt(0)
	s_barrier
; #define GLOAD(dst, kt_) _Pragma("unroll") for (int i = 0; i < NCH; ++i) { dst[i] = (i < NCHW) ? ldw(i, tid >> 3, (kt_) * 64 + (tid & 7) * 8) : ldx(i - NCHW, tid >> 3, (kt_) * 64 + (tid & 7) * 8); }
; #define LSTORE(src, base) _Pragma("unroll") for (int i = 0; i < NCH; ++i) { const int c = tid + 256 * i; *(u32x4*)((base) + (c >> 3) * 144 + (c & 7) * 16) = src[i]; }
; template <int WGN, int INS, int IMS, bool DB, class LdW, class LdX>
; DI void gemm_core(f32x16 (&acc)[INS][IMS], const int KT, LdW ldw, LdX ldx, char* lds, const int tid) {
;     ...
;     for (int kt = 0; kt < KT; kt += 2) {
;       if (kt + 2 < KT) { GLOAD(preA, kt + 2) }
;       COMPUTE_PIPE(lds)
;       LSTORE(preB, lds + BUFB)
;       __syncthreads();
;       if (kt + 3 < KT) { GLOAD(preB, kt + 3) }
;       COMPUTE_PIPE(lds + BUFB)
;       if (kt + 2 < KT) { LSTORE(preA, lds) }
;       __syncthreads();
;     }
	v_mfma_f32_32x32x16_bf16 v[0:15], v[118:121], v[134:137], v[0:15]
	ds_read_b128 v[110:113], v64
	ds_read_b128 v[114:117], v67 offset:18432
	ds_read_b128 v[118:121], v64 offset:32
	ds_read_b128 v[122:125], v67 offset:18464
	ds_read_b128 v[126:129], v64 offset:4608
	ds_read_b128 v[130:133], v64 offset:4640
	s_waitcnt lgkmcnt(4)
	v_mfma_f32_32x32x16_bf16 v[48:63], v[110:113], v[114:117], v[48:63]
	s_waitcnt lgkmcnt(1)
	v_mfma_f32_32x32x16_bf16 v[32:47], v[126:129], v[114:117], v[32:47]
	ds_read_b128 v[114:117], v67 offset:23040
	ds_read_b128 v[134:137], v67 offset:23072
	s_waitcnt lgkmcnt(1)
	v_mfma_f32_32x32x16_bf16 v[16:31], v[110:113], v[114:117], v[16:31]
	v_mfma_f32_32x32x16_bf16 v[0:15], v[126:129], v[114:117], v[0:15]
	v_mfma_f32_32x32x16_bf16 v[48:63], v[118:121], v[122:125], v[48:63]
	v_mfma_f32_32x32x16_bf16 v[32:47], v[130:133], v[122:125], v[32:47]
	s_waitcnt lgkmcnt(0)
	v_mfma_f32_32x32x16_bf16 v[16:31], v[118:121], v[134:137], v[16:31]
	ds_read_b128 v[110:113], v64 offset:64
	ds_read_b128 v[114:117], v67 offset:18496
	ds_read_b128 v[118:121], v64 offset:96
	ds_read_b128 v[122:125], v67 offset:18528
	v_mfma_f32_32x32x16_bf16 v[0:15], v[130:133], v[134:137], v[0:15]
	ds_read_b128 v[126:129], v64 offset:4672
	ds_read_b128 v[130:133], v64 offset:4704
	s_waitcnt lgkmcnt(4)
	v_mfma_f32_32x32x16_bf16 v[48:63], v[110:113], v[114:117], v[48:63]
	s_waitcnt lgkmcnt(1)
	v_mfma_f32_32x32x16_bf16 v[32:47], v[126:129], v[114:117], v[32:47]
	ds_read_b128 v[114:117], v67 offset:23104
	ds_read_b128 v[134:137], v67 offset:23136
	s_waitcnt lgkmcnt(1)
	v_mfma_f32_32x32x16_bf16 v[16:31], v[110:113], v[114:117], v[16:31]
	v_or_b32_e32 v110, 0x180, v178
	v_mov_b32_e32 v111, v179
	v_lshlrev_b64 v[154:155], 1, v[110:111]
	v_lshl_add_u64 v[110:111], s[0:1], 0, v[154:155]
	v_lshl_add_u64 v[150:151], s[4:5], 0, v[154:155]
	v_lshl_add_u64 v[152:153], s[6:7], 0, v[154:155]
	v_lshl_add_u64 v[156:157], s[8:9], 0, v[154:155]
	v_mfma_f32_32x32x16_bf16 v[0:15], v[126:129], v[114:117], v[0:15]
	v_lshl_add_u64 v[114:115], s[2:3], 0, v[154:155]
	v_lshl_add_u64 v[158:159], s[10:11], 0, v[154:155]
	global_load_dwordx4 v[110:113], v[110:111], off
	s_nop 0
	global_load_dwordx4 v[114:117], v[114:115], off
	v_mfma_f32_32x32x16_bf16 v[48:63], v[118:121], v[122:125], v[48:63]
	v_mfma_f32_32x32x16_bf16 v[32:47], v[130:133], v[122:125], v[32:47]
	global_load_dwordx4 v[122:125], v[72:73], off offset:768
	global_load_dwordx4 v[126:129], v[84:85], off offset:768
	s_waitcnt lgkmcnt(0)
	v_mfma_f32_32x32x16_bf16 v[16:31], v[118:121], v[134:137], v[16:31]
	global_load_dwordx4 v[118:121], v[150:151], off
	s_nop 0
	global_load_dwordx4 v[150:153], v[152:153], off
	s_nop 0
	global_load_dwordx4 v[154:157], v[156:157], off
	s_nop 0
	global_load_dwordx4 v[158:161], v[158:159], off
	s_waitcnt vmcnt(13)
	ds_write_b128 v66, v[102:105] offset:36864
	ds_write_b128 v68, v[90:93] offset:36864
	ds_write_b128 v70, v[94:97] offset:36864
	s_waitcnt vmcnt(11)
	ds_write_b128 v74, v[98:101] offset:36864
	ds_write_b128 v76, v[106:109] offset:36864
	s_waitcnt vmcnt(10)
	ds_write_b128 v78, v[138:141] offset:36864
	s_waitcnt vmcnt(9)
	ds_write_b128 v80, v[142:145] offset:36864
	s_waitcnt vmcnt(8)
	ds_write_b128 v82, v[146:149] offset:36864
	s_waitcnt lgkmcnt(0)
	s_barrier
	ds_read_b128 v[90:93], v64 offset:36864
	ds_read_b128 v[94:97], v67 offset:55296
	ds_read_b128 v[98:101], v64 offset:36896
	ds_read_b128 v[102:105], v67 offset:55328
	v_mfma_f32_32x32x16_bf16 v[0:15], v[130:133], v[134:137], v[0:15]
	ds_read_b128 v[106:109], v64 offset:41472
	ds_read_b128 v[130:133], v64 offset:41504
	s_waitcnt lgkmcnt(4)
	v_mfma_f32_32x32x16_bf16 v[48:63], v[90:93], v[94:97], v[48:63]
	s_waitcnt lgkmcnt(1)
	v_mfma_f32_32x32x16_bf16 v[32:47], v[106:109], v[94:97], v[32:47]
	ds_read_b128 v[94:97], v67 offset:59904
	ds_read_b128 v[134:137], v67 offset:59936
	s_waitcnt lgkmcnt(1)
	v_mfma_f32_32x32x16_bf16 v[16:31], v[90:93], v[94:97], v[16:31]
	v_mfma_f32_32x32x16_bf16 v[0:15], v[106:109], v[94:97], v[0:15]
	v_mfma_f32_32x32x16_bf16 v[48:63], v[98:101], v[102:105], v[48:63]
	v_mfma_f32_32x32x16_bf16 v[32:47], v[130:133], v[102:105], v[32:47]
	s_waitcnt lgkmcnt(0)
	v_mfma_f32_32x32x16_bf16 v[16:31], v[98:101], v[134:137], v[16:31]
	ds_read_b128 v[90:93], v64 offset:36928
	ds_read_b128 v[94:97], v67 offset:55360
	ds_read_b128 v[98:101], v64 offset:36960
	ds_read_b128 v[102:105], v67 offset:55392
	v_mfma_f32_32x32x16_bf16 v[0:15], v[130:133], v[134:137], v[0:15]
	ds_read_b128 v[106:109], v64 offset:41536
	ds_read_b128 v[130:133], v64 offset:41568
	s_waitcnt lgkmcnt(4)
	v_mfma_f32_32x32x16_bf16 v[48:63], v[90:93], v[94:97], v[48:63]
	s_waitcnt lgkmcnt(1)
	v_mfma_f32_32x32x16_bf16 v[32:47], v[106:109], v[94:97], v[32:47]
	ds_read_b128 v[94:97], v67 offset:59968
	ds_read_b128 v[134:137], v67 offset:60000
	s_waitcnt lgkmcnt(1)
	v_mfma_f32_32x32x16_bf16 v[16:31], v[90:93], v[94:97], v[16:31]
	v_or_b32_e32 v90, 0x1c0, v178
	v_mov_b32_e32 v91, v179
	v_lshlrev_b64 v[142:143], 1, v[90:91]
	v_lshl_add_u64 v[90:91], s[0:1], 0, v[142:143]
	v_lshl_add_u64 v[138:139], s[4:5], 0, v[142:143]
	v_lshl_add_u64 v[140:141], s[6:7], 0, v[142:143]
	v_lshl_add_u64 v[144:145], s[8:9], 0, v[142:143]
	v_mfma_f32_32x32x16_bf16 v[0:15], v[106:109], v[94:97], v[0:15]
	v_lshl_add_u64 v[94:95], s[2:3], 0, v[142:143]
	v_lshl_add_u64 v[146:147], s[10:11], 0, v[142:143]
	global_load_dwordx4 v[90:93], v[90:91], off
	s_nop 0
	global_load_dwordx4 v[94:97], v[94:95], off
	v_mfma_f32_32x32x16_bf16 v[48:63], v[98:101], v[102:105], v[48:63]
	v_mfma_f32_32x32x16_bf16 v[32:47], v[130:133], v[102:105], v[32:47]
	global_load_dwordx4 v[102:105], v[72:73], off offset:896
	global_load_dwordx4 v[106:109], v[84:85], off offset:896
	s_waitcnt lgkmcnt(0)
	v_mfma_f32_32x32x16_bf16 v[16:31], v[98:101], v[134:137], v[16:31]
	global_load_dwordx4 v[98:101], v[138:139], off
	s_nop 0
	global_load_dwordx4 v[138:141], v[140:141], off
	s_nop 0
	global_load_dwordx4 v[142:145], v[144:145], off
	s_nop 0
	global_load_dwordx4 v[146:149], v[146:147], off
	s_waitcnt vmcnt(13)
	ds_write_b128 v66, v[122:125]
	ds_write_b128 v68, v[110:113]
	ds_write_b128 v70, v[114:117]
	s_waitcnt vmcnt(11)
	ds_write_b128 v74, v[118:121]
	ds_write_b128 v76, v[126:129]
	s_waitcnt vmcnt(10)
	ds_write_b128 v78, v[150:153]
	s_waitcnt vmcnt(9)
	ds_write_b128 v80, v[154:157]
	s_waitcnt vmcnt(8)
	ds_write_b128 v82, v[158:161]
	s_waitcnt lgkmcnt(0)
	s_barrier
; #define GLOAD(dst, kt_) _Pragma("unroll") for (int i = 0; i < NCH; ++i) { dst[i] = (i < NCHW) ? ldw(i, tid >> 3, (kt_) * 64 + (tid & 7) * 8) : ldx(i - NCHW, tid >> 3, (kt_) * 64 + (tid & 7) * 8); }
; #define LSTORE(src, base) _Pragma("unroll") for (int i = 0; i < NCH; ++i) { const int c = tid + 256 * i; *(u32x4*)((base) + (c >> 3) * 144 + (c & 7) * 16) = src[i]; }
; template <int WGN, int INS, int IMS, bool DB, class LdW, class LdX>
; DI void gemm_core(f32x16 (&acc)[INS][IMS], const int KT, LdW ldw, LdX ldx, char* lds, const int tid) {
;     ...
;     for (int kt = 0; kt < KT; kt += 2) {
;       if (kt + 2 < KT) { GLOAD(preA, kt + 2) }
;       COMPUTE_PIPE(lds)
;       LSTORE(preB, lds + BUFB)
;       __syncthreads();
;       if (kt + 3 < KT) { GLOAD(preB, kt + 3) }
;       COMPUTE_PIPE(lds + BUFB)
;       if (kt + 2 < KT) { LSTORE(preA, lds) }
;       __syncthreads();
;     }
	ds_read_b128 v[110:113], v64
	ds_read_b128 v[114:117], v67 offset:18432
	ds_read_b128 v[118:121], v64 offset:32
	ds_read_b128 v[122:125], v67 offset:18464
	v_mfma_f32_32x32x16_bf16 v[0:15], v[130:133], v[134:137], v[0:15]
	ds_read_b128 v[126:129], v64 offset:4608
	ds_read_b128 v[130:133], v64 offset:4640
	s_waitcnt lgkmcnt(4)
	v_mfma_f32_32x32x16_bf16 v[48:63], v[110:113], v[114:117], v[48:63]
	s_waitcnt lgkmcnt(1)
	v_mfma_f32_32x32x16_bf16 v[32:47], v[126:129], v[114:117], v[32:47]
	ds_read_b128 v[114:117], v67 offset:23040
	ds_read_b128 v[134:137], v67 offset:23072
	s_waitcnt lgkmcnt(1)
	v_mfma_f32_32x32x16_bf16 v[16:31], v[110:113], v[114:117], v[16:31]
	v_mfma_f32_32x32x16_bf16 v[0:15], v[126:129], v[114:117], v[0:15]
	v_mfma_f32_32x32x16_bf16 v[48:63], v[118:121], v[122:125], v[48:63]
	v_mfma_f32_32x32x16_bf16 v[32:47], v[130:133], v[122:125], v[32:47]
	s_waitcnt lgkmcnt(0)
	v_mfma_f32_32x32x16_bf16 v[16:31], v[118:121], v[134:137], v[16:31]
	ds_read_b128 v[110:113], v64 offset:64
	ds_read_b128 v[114:117], v67 offset:18496
	ds_read_b128 v[118:121], v64 offset:96
	ds_read_b128 v[122:125], v67 offset:18528
	v_mfma_f32_32x32x16_bf16 v[0:15], v[130:133], v[134:137], v[0:15]
	ds_read_b128 v[126:129], v64 offset:4672
	ds_read_b128 v[130:133], v64 offset:4704
	s_waitcnt lgkmcnt(4)
	v_mfma_f32_32x32x16_bf16 v[48:63], v[110:113], v[114:117], v[48:63]
	s_waitcnt lgkmcnt(1)
	v_mfma_f32_32x32x16_bf16 v[32:47], v[126:129], v[114:117], v[32:47]
	ds_read_b128 v[114:117], v67 offset:23104
	ds_read_b128 v[134:137], v67 offset:23136
	s_waitcnt lgkmcnt(1)
	v_mfma_f32_32x32x16_bf16 v[16:31], v[110:113], v[114:117], v[16:31]
	v_or_b32_e32 v110, 0x200, v178
	v_mov_b32_e32 v111, v179
	v_lshlrev_b64 v[154:155], 1, v[110:111]
	v_lshl_add_u64 v[110:111], s[0:1], 0, v[154:155]
	v_lshl_add_u64 v[150:151], s[4:5], 0, v[154:155]
	v_lshl_add_u64 v[152:153], s[6:7], 0, v[154:155]
	v_lshl_add_u64 v[156:157], s[8:9], 0, v[154:155]
	v_mfma_f32_32x32x16_bf16 v[0:15], v[126:129], v[114:117], v[0:15]
	v_lshl_add_u64 v[114:115], s[2:3], 0, v[154:155]
	v_lshl_add_u64 v[158:159], s[10:11], 0, v[154:155]
	global_load_dwordx4 v[110:113], v[110:111], off
	s_nop 0
	global_load_dwordx4 v[114:117], v[114:115], off
	v_mfma_f32_32x32x16_bf16 v[48:63], v[118:121], v[122:125], v[48:63]
	v_mfma_f32_32x32x16_bf16 v[32:47], v[130:133], v[122:125], v[32:47]
	global_load_dwordx4 v[122:125], v[72:73], off offset:1024
	global_load_dwordx4 v[126:129], v[84:85], off offset:1024
	s_waitcnt lgkmcnt(0)
	v_mfma_f32_32x32x16_bf16 v[16:31], v[118:121], v[134:137], v[16:31]
	global_load_dwordx4 v[118:121], v[150:151], off
	s_nop 0
	global_load_dwordx4 v[150:153], v[152:153], off
	s_nop 0
	global_load_dwordx4 v[154:157], v[156:157], off
	s_nop 0
	global_load_dwordx4 v[158:161], v[158:159], off
	s_waitcnt vmcnt(13)
	ds_write_b128 v66, v[102:105] offset:36864
	ds_write_b128 v68, v[90:93] offset:36864
	ds_write_b128 v70, v[94:97] offset:36864
	s_waitcnt vmcnt(11)
	ds_write_b128 v74, v[98:101] offset:36864
	ds_write_b128 v76, v[106:109] offset:36864
	s_waitcnt vmcnt(10)
	ds_write_b128 v78, v[138:141] offset:36864
	s_waitcnt vmcnt(9)
	ds_write_b128 v80, v[142:145] offset:36864
	s_waitcnt vmcnt(8)
	ds_write_b128 v82, v[146:149] offset:36864
	s_waitcnt lgkmcnt(0)
	s_barrier
	ds_read_b128 v[90:93], v64 offset:36864
	ds_read_b128 v[94:97], v67 offset:55296
	ds_read_b128 v[98:101], v64 offset:36896
	ds_read_b128 v[102:105], v67 offset:55328
	v_mfma_f32_32x32x16_bf16 v[0:15], v[130:133], v[134:137], v[0:15]
	ds_read_b128 v[106:109], v64 offset:41472
	ds_read_b128 v[130:133], v64 offset:41504
	s_waitcnt lgkmcnt(4)
	v_mfma_f32_32x32x16_bf16 v[48:63], v[90:93], v[94:97], v[48:63]
	s_waitcnt lgkmcnt(1)
	v_mfma_f32_32x32x16_bf16 v[32:47], v[106:109], v[94:97], v[32:47]
	ds_read_b128 v[94:97], v67 offset:59904
	ds_read_b128 v[134:137], v67 offset:59936
	s_waitcnt lgkmcnt(1)
	v_mfma_f32_32x32x16_bf16 v[16:31], v[90:93], v[94:97], v[16:31]
	v_mfma_f32_32x32x16_bf16 v[0:15], v[106:109], v[94:97], v[0:15]
	v_mfma_f32_32x32x16_bf16 v[48:63], v[98:101], v[102:105], v[48:63]
	v_mfma_f32_32x32x16_bf16 v[32:47], v[130:133], v[102:105], v[32:47]
	s_waitcnt lgkmcnt(0)
	v_mfma_f32_32x32x16_bf16 v[16:31], v[98:101], v[134:137], v[16:31]
	ds_read_b128 v[90:93], v64 offset:36928
	ds_read_b128 v[94:97], v67 offset:55360
	ds_read_b128 v[98:101], v64 offset:36960
	ds_read_b128 v[102:105], v67 offset:55392
	v_mfma_f32_32x32x16_bf16 v[0:15], v[130:133], v[134:137], v[0:15]
	ds_read_b128 v[106:109], v64 offset:41536
	ds_read_b128 v[130:133], v64 offset:41568
	s_waitcnt lgkmcnt(4)
	v_mfma_f32_32x32x16_bf16 v[48:63], v[90:93], v[94:97], v[48:63]
	s_waitcnt lgkmcnt(1)
	v_mfma_f32_32x32x16_bf16 v[32:47], v[106:109], v[94:97], v[32:47]
	ds_read_b128 v[94:97], v67 offset:59968
	ds_read_b128 v[134:137], v67 offset:60000
	s_waitcnt lgkmcnt(1)
	v_mfma_f32_32x32x16_bf16 v[16:31], v[90:93], v[94:97], v[16:31]
	v_or_b32_e32 v90, 0x240, v178
	v_mov_b32_e32 v91, v179
	v_lshlrev_b64 v[142:143], 1, v[90:91]
	v_lshl_add_u64 v[90:91], s[0:1], 0, v[142:143]
	v_lshl_add_u64 v[138:139], s[4:5], 0, v[142:143]
	v_lshl_add_u64 v[140:141], s[6:7], 0, v[142:143]
	v_lshl_add_u64 v[144:145], s[8:9], 0, v[142:143]
	v_mfma_f32_32x32x16_bf16 v[0:15], v[106:109], v[94:97], v[0:15]
	v_lshl_add_u64 v[94:95], s[2:3], 0, v[142:143]
	v_lshl_add_u64 v[146:147], s[10:11], 0, v[142:143]
	global_load_dwordx4 v[90:93], v[90:91], off
	s_nop 0
	global_load_dwordx4 v[94:97], v[94:95], off
	v_mfma_f32_32x32x16_bf16 v[48:63], v[98:101], v[102:105], v[48:63]
	v_mfma_f32_32x32x16_bf16 v[32:47], v[130:133], v[102:105], v[32:47]
	global_load_dwordx4 v[102:105], v[72:73], off offset:1152
	global_load_dwordx4 v[106:109], v[84:85], off offset:1152
	s_waitcnt lgkmcnt(0)
	v_mfma_f32_32x32x16_bf16 v[16:31], v[98:101], v[134:137], v[16:31]
	global_load_dwordx4 v[98:101], v[138:139], off
	s_nop 0
	global_load_dwordx4 v[138:141], v[140:141], off
	s_nop 0
	global_load_dwordx4 v[142:145], v[144:145], off
	s_nop 0
	global_load_dwordx4 v[146:149], v[146:147], off
	s_waitcnt vmcnt(13)
	ds_write_b128 v66, v[122:125]
	ds_write_b128 v68, v[110:113]
	ds_write_b128 v70, v[114:117]
	s_waitcnt vmcnt(11)
	ds_write_b128 v74, v[118:121]
	ds_write_b128 v76, v[126:129]
	s_waitcnt vmcnt(10)
	ds_write_b128 v78, v[150:153]
	s_waitcnt vmcnt(9)
	ds_write_b128 v80, v[154:157]
	s_waitcnt vmcnt(8)
	ds_write_b128 v82, v[158:161]
	s_waitcnt lgkmcnt(0)
	s_barrier
; #define GLOAD(dst, kt_) _Pragma("unroll") for (int i = 0; i < NCH; ++i) { dst[i] = (i < NCHW) ? ldw(i, tid >> 3, (kt_) * 64 + (tid & 7) * 8) : ldx(i - NCHW, tid >> 3, (kt_) * 64 + (tid & 7) * 8); }
; #define LSTORE(src, base) _Pragma("unroll") for (int i = 0; i < NCH; ++i) { const int c = tid + 256 * i; *(u32x4*)((base) + (c >> 3) * 144 + (c & 7) * 16) = src[i]; }
; template <int WGN, int INS, int IMS, bool DB, class LdW, class LdX>
; DI void gemm_core(f32x16 (&acc)[INS][IMS], const int KT, LdW ldw, LdX ldx, char* lds, const int tid) {
;     ...
;     for (int kt = 0; kt < KT; kt += 2) {
;       if (kt + 2 < KT) { GLOAD(preA, kt + 2) }
;       COMPUTE_PIPE(lds)
;       LSTORE(preB, lds + BUFB)
;       __syncthreads();
;       if (kt + 3 < KT) { GLOAD(preB, kt + 3) }
;       COMPUTE_PIPE(lds + BUFB)
;       if (kt + 2 < KT) { LSTORE(preA, lds) }
;       __syncthreads();
;     }
	ds_read_b128 v[110:113], v64
	ds_read_b128 v[114:117], v67 offset:18432
	ds_read_b128 v[118:121], v64 offset:32
	ds_read_b128 v[122:125], v67 offset:18464
	v_mfma_f32_32x32x16_bf16 v[0:15], v[130:133], v[134:137], v[0:15]
	ds_read_b128 v[126:129], v64 offset:4608
	ds_read_b128 v[130:133], v64 offset:4640
	s_waitcnt lgkmcnt(4)
	v_mfma_f32_32x32x16_bf16 v[48:63], v[110:113], v[114:117], v[48:63]
	s_waitcnt lgkmcnt(1)
	v_mfma_f32_32x32x16_bf16 v[32:47], v[126:129], v[114:117], v[32:47]
	ds_read_b128 v[114:117], v67 offset:23040
	ds_read_b128 v[134:137], v67 offset:23072
	s_waitcnt lgkmcnt(1)
	v_mfma_f32_32x32x16_bf16 v[16:31], v[110:113], v[114:117], v[16:31]
	v_mfma_f32_32x32x16_bf16 v[0:15], v[126:129], v[114:117], v[0:15]
	v_mfma_f32_32x32x16_bf16 v[48:63], v[118:121], v[122:125], v[48:63]
	v_mfma_f32_32x32x16_bf16 v[32:47], v[130:133], v[122:125], v[32:47]
	s_waitcnt lgkmcnt(0)
	v_mfma_f32_32x32x16_bf16 v[16:31], v[118:121], v[134:137], v[16:31]
	ds_read_b128 v[110:113], v64 offset:64
	ds_read_b128 v[114:117], v67 offset:18496
	ds_read_b128 v[118:121], v64 offset:96
	ds_read_b128 v[122:125], v67 offset:18528
	v_mfma_f32_32x32x16_bf16 v[0:15], v[130:133], v[134:137], v[0:15]
	ds_read_b128 v[126:129], v64 offset:4672
	ds_read_b128 v[130:133], v64 offset:4704
	s_waitcnt lgkmcnt(4)
	v_mfma_f32_32x32x16_bf16 v[48:63], v[110:113], v[114:117], v[48:63]
	s_waitcnt lgkmcnt(1)
	v_mfma_f32_32x32x16_bf16 v[32:47], v[126:129], v[114:117], v[32:47]
	ds_read_b128 v[114:117], v67 offset:23104
	ds_read_b128 v[134:137], v67 offset:23136
	s_waitcnt lgkmcnt(1)
	v_mfma_f32_32x32x16_bf16 v[16:31], v[110:113], v[114:117], v[16:31]
	v_or_b32_e32 v110, 0x280, v178
	v_mov_b32_e32 v111, v179
	v_lshlrev_b64 v[154:155], 1, v[110:111]
	v_lshl_add_u64 v[110:111], s[0:1], 0, v[154:155]
	v_lshl_add_u64 v[150:151], s[4:5], 0, v[154:155]
	v_lshl_add_u64 v[152:153], s[6:7], 0, v[154:155]
	v_lshl_add_u64 v[156:157], s[8:9], 0, v[154:155]
	v_mfma_f32_32x32x16_bf16 v[0:15], v[126:129], v[114:117], v[0:15]
	v_lshl_add_u64 v[114:115], s[2:3], 0, v[154:155]
	v_lshl_add_u64 v[158:159], s[10:11], 0, v[154:155]
	global_load_dwordx4 v[110:113], v[110:111], off
	s_nop 0
	global_load_dwordx4 v[114:117], v[114:115], off
	v_mfma_f32_32x32x16_bf16 v[48:63], v[118:121], v[122:125], v[48:63]
	v_mfma_f32_32x32x16_bf16 v[32:47], v[130:133], v[122:125], v[32:47]
	global_load_dwordx4 v[122:125], v[72:73], off offset:1280
	global_load_dwordx4 v[126:129], v[84:85], off offset:1280
	s_waitcnt lgkmcnt(0)
	v_mfma_f32_32x32x16_bf16 v[16:31], v[118:121], v[134:137], v[16:31]
	global_load_dwordx4 v[118:121], v[150:151], off
	s_nop 0
	global_load_dwordx4 v[150:153], v[152:153], off
	s_nop 0
	global_load_dwordx4 v[154:157], v[156:157], off
	s_nop 0
	global_load_dwordx4 v[158:161], v[158:159], off
	s_waitcnt vmcnt(13)
	ds_write_b128 v66, v[102:105] offset:36864
	ds_write_b128 v68, v[90:93] offset:36864
	ds_write_b128 v70, v[94:97] offset:36864
	s_waitcnt vmcnt(11)
	ds_write_b128 v74, v[98:101] offset:36864
	ds_write_b128 v76, v[106:109] offset:36864
	s_waitcnt vmcnt(10)
	ds_write_b128 v78, v[138:141] offset:36864
	s_waitcnt vmcnt(9)
	ds_write_b128 v80, v[142:145] offset:36864
	s_waitcnt vmcnt(8)
	ds_write_b128 v82, v[146:149] offset:36864
	s_waitcnt lgkmcnt(0)
	s_barrier
	ds_read_b128 v[90:93], v64 offset:36864
	ds_read_b128 v[94:97], v67 offset:55296
	ds_read_b128 v[98:101], v64 offset:36896
	ds_read_b128 v[102:105], v67 offset:55328
	v_mfma_f32_32x32x16_bf16 v[0:15], v[130:133], v[134:137], v[0:15]
	ds_read_b128 v[106:109], v64 offset:41472
	ds_read_b128 v[130:133], v64 offset:41504
	s_waitcnt lgkmcnt(4)
	v_mfma_f32_32x32x16_bf16 v[48:63], v[90:93], v[94:97], v[48:63]
	s_waitcnt lgkmcnt(1)
	v_mfma_f32_32x32x16_bf16 v[32:47], v[106:109], v[94:97], v[32:47]
	ds_read_b128 v[94:97], v67 offset:59904
	ds_read_b128 v[134:137], v67 offset:59936
	s_waitcnt lgkmcnt(1)
	v_mfma_f32_32x32x16_bf16 v[16:31], v[90:93], v[94:97], v[16:31]
	v_mfma_f32_32x32x16_bf16 v[0:15], v[106:109], v[94:97], v[0:15]
	v_mfma_f32_32x32x16_bf16 v[48:63], v[98:101], v[102:105], v[48:63]
	v_mfma_f32_32x32x16_bf16 v[32:47], v[130:133], v[102:105], v[32:47]
	s_waitcnt lgkmcnt(0)
	v_mfma_f32_32x32x16_bf16 v[16:31], v[98:101], v[134:137], v[16:31]
	ds_read_b128 v[90:93], v64 offset:36928
	ds_read_b128 v[94:97], v67 offset:55360
	ds_read_b128 v[98:101], v64 offset:36960
	ds_read_b128 v[102:105], v67 offset:55392
	v_mfma_f32_32x32x16_bf16 v[0:15], v[130:133], v[134:137], v[0:15]
	ds_read_b128 v[106:109], v64 offset:41536
	ds_read_b128 v[130:133], v64 offset:41568
	s_waitcnt lgkmcnt(4)
	v_mfma_f32_32x32x16_bf16 v[48:63], v[90:93], v[94:97], v[48:63]
	s_waitcnt lgkmcnt(1)
	v_mfma_f32_32x32x16_bf16 v[32:47], v[106:109], v[94:97], v[32:47]
	ds_read_b128 v[94:97], v67 offset:59968
	ds_read_b128 v[134:137], v67 offset:60000
	s_waitcnt lgkmcnt(1)
	v_mfma_f32_32x32x16_bf16 v[16:31], v[90:93], v[94:97], v[16:31]
	v_or_b32_e32 v90, 0x2c0, v178
	v_mov_b32_e32 v91, v179
	v_lshlrev_b64 v[142:143], 1, v[90:91]
	v_lshl_add_u64 v[90:91], s[0:1], 0, v[142:143]
	v_lshl_add_u64 v[138:139], s[4:5], 0, v[142:143]
	v_lshl_add_u64 v[140:141], s[6:7], 0, v[142:143]
	v_lshl_add_u64 v[144:145], s[8:9], 0, v[142:143]
	v_mfma_f32_32x32x16_bf16 v[0:15], v[106:109], v[94:97], v[0:15]
	v_lshl_add_u64 v[94:95], s[2:3], 0, v[142:143]
	v_lshl_add_u64 v[146:147], s[10:11], 0, v[142:143]
	global_load_dwordx4 v[90:93], v[90:91], off
	s_nop 0
	global_load_dwordx4 v[94:97], v[94:95], off
	v_mfma_f32_32x32x16_bf16 v[48:63], v[98:101], v[102:105], v[48:63]
	v_mfma_f32_32x32x16_bf16 v[32:47], v[130:133], v[102:105], v[32:47]
	global_load_dwordx4 v[102:105], v[72:73], off offset:1408
	global_load_dwordx4 v[106:109], v[84:85], off offset:1408
	s_waitcnt lgkmcnt(0)
	v_mfma_f32_32x32x16_bf16 v[16:31], v[98:101], v[134:137], v[16:31]
	global_load_dwordx4 v[98:101], v[138:139], off
	s_nop 0
	global_load_dwordx4 v[138:141], v[140:141], off
	s_nop 0
	global_load_dwordx4 v[142:145], v[144:145], off
	s_nop 0
	global_load_dwordx4 v[146:149], v[146:147], off
	s_waitcnt vmcnt(13)
	ds_write_b128 v66, v[122:125]
	ds_write_b128 v68, v[110:113]
	ds_write_b128 v70, v[114:117]
	s_waitcnt vmcnt(11)
	ds_write_b128 v74, v[118:121]
	ds_write_b128 v76, v[126:129]
	s_waitcnt vmcnt(10)
	ds_write_b128 v78, v[150:153]
	s_waitcnt vmcnt(9)
	ds_write_b128 v80, v[154:157]
	s_waitcnt vmcnt(8)
	ds_write_b128 v82, v[158:161]
	s_waitcnt lgkmcnt(0)
	s_barrier
; #define GLOAD(dst, kt_) _Pragma("unroll") for (int i = 0; i < NCH; ++i) { dst[i] = (i < NCHW) ? ldw(i, tid >> 3, (kt_) * 64 + (tid & 7) * 8) : ldx(i - NCHW, tid >> 3, (kt_) * 64 + (tid & 7) * 8); }
; #define LSTORE(src, base) _Pragma("unroll") for (int i = 0; i < NCH; ++i) { const int c = tid + 256 * i; *(u32x4*)((base) + (c >> 3) * 144 + (c & 7) * 16) = src[i]; }
; template <int WGN, int INS, int IMS, bool DB, class LdW, class LdX>
; DI void gemm_core(f32x16 (&acc)[INS][IMS], const int KT, LdW ldw, LdX ldx, char* lds, const int tid) {
;     ...
;     for (int kt = 0; kt < KT; kt += 2) {
;       if (kt + 2 < KT) { GLOAD(preA, kt + 2) }
;       COMPUTE_PIPE(lds)
;       LSTORE(preB, lds + BUFB)
;       __syncthreads();
;       if (kt + 3 < KT) { GLOAD(preB, kt + 3) }
;       COMPUTE_PIPE(lds + BUFB)
;       if (kt + 2 < KT) { LSTORE(preA, lds) }
;       __syncthreads();
;     }
	ds_read_b128 v[110:113], v64
	ds_read_b128 v[114:117], v67 offset:18432
	ds_read_b128 v[118:121], v64 offset:32
	ds_read_b128 v[122:125], v67 offset:18464
	v_mfma_f32_32x32x16_bf16 v[0:15], v[130:133], v[134:137], v[0:15]
	ds_read_b128 v[126:129], v64 offset:4608
	ds_read_b128 v[130:133], v64 offset:4640
	s_waitcnt lgkmcnt(4)
	v_mfma_f32_32x32x16_bf16 v[48:63], v[110:113], v[114:117], v[48:63]
	s_waitcnt lgkmcnt(1)
	v_mfma_f32_32x32x16_bf16 v[32:47], v[126:129], v[114:117], v[32:47]
	ds_read_b128 v[114:117], v67 offset:23040
	ds_read_b128 v[134:137], v67 offset:23072
	s_waitcnt lgkmcnt(1)
	v_mfma_f32_32x32x16_bf16 v[16:31], v[110:113], v[114:117], v[16:31]
	v_mfma_f32_32x32x16_bf16 v[0:15], v[126:129], v[114:117], v[0:15]
	v_mfma_f32_32x32x16_bf16 v[48:63], v[118:121], v[122:125], v[48:63]
	v_mfma_f32_32x32x16_bf16 v[32:47], v[130:133], v[122:125], v[32:47]
	s_waitcnt lgkmcnt(0)
	v_mfma_f32_32x32x16_bf16 v[16:31], v[118:121], v[134:137], v[16:31]
	ds_read_b128 v[110:113], v64 offset:64
	ds_read_b128 v[114:117], v67 offset:18496
	ds_read_b128 v[118:121], v64 offset:96
	ds_read_b128 v[122:125], v67 offset:18528
	v_mfma_f32_32x32x16_bf16 v[0:15], v[130:133], v[134:137], v[0:15]
	ds_read_b128 v[126:129], v64 offset:4672
	ds_read_b128 v[130:133], v64 offset:4704
	s_waitcnt lgkmcnt(4)
	v_mfma_f32_32x32x16_bf16 v[48:63], v[110:113], v[114:117], v[48:63]
	s_waitcnt lgkmcnt(1)
	v_mfma_f32_32x32x16_bf16 v[32:47], v[126:129], v[114:117], v[32:47]
	ds_read_b128 v[114:117], v67 offset:23104
	ds_read_b128 v[134:137], v67 offset:23136
	s_waitcnt lgkmcnt(1)
	v_mfma_f32_32x32x16_bf16 v[16:31], v[110:113], v[114:117], v[16:31]
	v_or_b32_e32 v110, 0x300, v178
	v_mov_b32_e32 v111, v179
	v_lshlrev_b64 v[154:155], 1, v[110:111]
	v_lshl_add_u64 v[110:111], s[0:1], 0, v[154:155]
	v_lshl_add_u64 v[150:151], s[4:5], 0, v[154:155]
	v_lshl_add_u64 v[152:153], s[6:7], 0, v[154:155]
	v_lshl_add_u64 v[156:157], s[8:9], 0, v[154:155]
	v_mfma_f32_32x32x16_bf16 v[0:15], v[126:129], v[114:117], v[0:15]
	v_lshl_add_u64 v[114:115], s[2:3], 0, v[154:155]
	v_lshl_add_u64 v[158:159], s[10:11], 0, v[154:155]
	global_load_dwordx4 v[110:113], v[110:111], off
	s_nop 0
	global_load_dwordx4 v[114:117], v[114:115], off
	v_mfma_f32_32x32x16_bf16 v[48:63], v[118:121], v[122:125], v[48:63]
	v_mfma_f32_32x32x16_bf16 v[32:47], v[130:133], v[122:125], v[32:47]
	global_load_dwordx4 v[122:125], v[72:73], off offset:1536
	global_load_dwordx4 v[126:129], v[84:85], off offset:1536
	s_waitcnt lgkmcnt(0)
	v_mfma_f32_32x32x16_bf16 v[16:31], v[118:121], v[134:137], v[16:31]
	global_load_dwordx4 v[118:121], v[150:151], off
	s_nop 0
	global_load_dwordx4 v[150:153], v[152:153], off
	s_nop 0
	global_load_dwordx4 v[154:157], v[156:157], off
	s_nop 0
	global_load_dwordx4 v[158:161], v[158:159], off
	s_waitcnt vmcnt(13)
	ds_write_b128 v66, v[102:105] offset:36864
	ds_write_b128 v68, v[90:93] offset:36864
	ds_write_b128 v70, v[94:97] offset:36864
	s_waitcnt vmcnt(11)
	ds_write_b128 v74, v[98:101] offset:36864
	ds_write_b128 v76, v[106:109] offset:36864
	s_waitcnt vmcnt(10)
	ds_write_b128 v78, v[138:141] offset:36864
	s_waitcnt vmcnt(9)
	ds_write_b128 v80, v[142:145] offset:36864
	s_waitcnt vmcnt(8)
	ds_write_b128 v82, v[146:149] offset:36864
	s_waitcnt lgkmcnt(0)
	s_barrier
	ds_read_b128 v[90:93], v64 offset:36864
	ds_read_b128 v[94:97], v67 offset:55296
	ds_read_b128 v[98:101], v64 offset:36896
	ds_read_b128 v[102:105], v67 offset:55328
	v_mfma_f32_32x32x16_bf16 v[0:15], v[130:133], v[134:137], v[0:15]
	ds_read_b128 v[106:109], v64 offset:41472
	ds_read_b128 v[130:133], v64 offset:41504
	s_waitcnt lgkmcnt(4)
	v_mfma_f32_32x32x16_bf16 v[48:63], v[90:93], v[94:97], v[48:63]
	s_waitcnt lgkmcnt(1)
	v_mfma_f32_32x32x16_bf16 v[32:47], v[106:109], v[94:97], v[32:47]
	ds_read_b128 v[94:97], v67 offset:59904
	ds_read_b128 v[134:137], v67 offset:59936
	s_waitcnt lgkmcnt(1)
	v_mfma_f32_32x32x16_bf16 v[16:31], v[90:93], v[94:97], v[16:31]
	v_mfma_f32_32x32x16_bf16 v[0:15], v[106:109], v[94:97], v[0:15]
	v_mfma_f32_32x32x16_bf16 v[48:63], v[98:101], v[102:105], v[48:63]
	v_mfma_f32_32x32x16_bf16 v[32:47], v[130:133], v[102:105], v[32:47]
	s_waitcnt lgkmcnt(0)
	v_mfma_f32_32x32x16_bf16 v[16:31], v[98:101], v[134:137], v[16:31]
	ds_read_b128 v[90:93], v64 offset:36928
	ds_read_b128 v[94:97], v67 offset:55360
	ds_read_b128 v[98:101], v64 offset:36960
	ds_read_b128 v[102:105], v67 offset:55392
	v_mfma_f32_32x32x16_bf16 v[0:15], v[130:133], v[134:137], v[0:15]
	ds_read_b128 v[106:109], v64 offset:41536
	ds_read_b128 v[130:133], v64 offset:41568
	s_waitcnt lgkmcnt(4)
	v_mfma_f32_32x32x16_bf16 v[48:63], v[90:93], v[94:97], v[48:63]
	s_waitcnt lgkmcnt(1)
	v_mfma_f32_32x32x16_bf16 v[32:47], v[106:109], v[94:97], v[32:47]
	ds_read_b128 v[94:97], v67 offset:59968
	ds_read_b128 v[134:137], v67 offset:60000
	s_waitcnt lgkmcnt(1)
	v_mfma_f32_32x32x16_bf16 v[16:31], v[90:93], v[94:97], v[16:31]
	v_or_b32_e32 v90, 0x340, v178
	v_mov_b32_e32 v91, v179
	v_lshlrev_b64 v[142:143], 1, v[90:91]
	v_lshl_add_u64 v[90:91], s[0:1], 0, v[142:143]
	v_lshl_add_u64 v[138:139], s[4:5], 0, v[142:143]
	v_lshl_add_u64 v[140:141], s[6:7], 0, v[142:143]
	v_lshl_add_u64 v[144:145], s[8:9], 0, v[142:143]
	v_mfma_f32_32x32x16_bf16 v[0:15], v[106:109], v[94:97], v[0:15]
	v_lshl_add_u64 v[94:95], s[2:3], 0, v[142:143]
	v_lshl_add_u64 v[146:147], s[10:11], 0, v[142:143]
	global_load_dwordx4 v[90:93], v[90:91], off
	s_nop 0
	global_load_dwordx4 v[94:97], v[94:95], off
	v_mfma_f32_32x32x16_bf16 v[48:63], v[98:101], v[102:105], v[48:63]
	v_mfma_f32_32x32x16_bf16 v[32:47], v[130:133], v[102:105], v[32:47]
	global_load_dwordx4 v[102:105], v[72:73], off offset:1664
	global_load_dwordx4 v[106:109], v[84:85], off offset:1664
	s_waitcnt lgkmcnt(0)
	v_mfma_f32_32x32x16_bf16 v[16:31], v[98:101], v[134:137], v[16:31]
	global_load_dwordx4 v[98:101], v[138:139], off
	s_nop 0
	global_load_dwordx4 v[138:141], v[140:141], off
	s_nop 0
	global_load_dwordx4 v[142:145], v[144:145], off
	s_nop 0
	global_load_dwordx4 v[146:149], v[146:147], off
	s_waitcnt vmcnt(13)
	ds_write_b128 v66, v[122:125]
	ds_write_b128 v68, v[110:113]
	ds_write_b128 v70, v[114:117]
	s_waitcnt vmcnt(11)
	ds_write_b128 v74, v[118:121]
	ds_write_b128 v76, v[126:129]
	s_waitcnt vmcnt(10)
	ds_write_b128 v78, v[150:153]
	s_waitcnt vmcnt(9)
	ds_write_b128 v80, v[154:157]
	s_waitcnt vmcnt(8)
	ds_write_b128 v82, v[158:161]
	s_waitcnt lgkmcnt(0)
	s_barrier
; #define GLOAD(dst, kt_) _Pragma("unroll") for (int i = 0; i < NCH; ++i) { dst[i] = (i < NCHW) ? ldw(i, tid >> 3, (kt_) * 64 + (tid & 7) * 8) : ldx(i - NCHW, tid >> 3, (kt_) * 64 + (tid & 7) * 8); }
; #define LSTORE(src, base) _Pragma("unroll") for (int i = 0; i < NCH; ++i) { const int c = tid + 256 * i; *(u32x4*)((base) + (c >> 3) * 144 + (c & 7) * 16) = src[i]; }
; template <int WGN, int INS, int IMS, bool DB, class LdW, class LdX>
; DI void gemm_core(f32x16 (&acc)[INS][IMS], const int KT, LdW ldw, LdX ldx, char* lds, const int tid) {
;     ...
;     for (int kt = 0; kt < KT; kt += 2) {
;       if (kt + 2 < KT) { GLOAD(preA, kt + 2) }
;       COMPUTE_PIPE(lds)
;       LSTORE(preB, lds + BUFB)
;       __syncthreads();
;       if (kt + 3 < KT) { GLOAD(preB, kt + 3) }
;       COMPUTE_PIPE(lds + BUFB)
;       if (kt + 2 < KT) { LSTORE(preA, lds) }
;       __syncthreads();
;     }
; template <int NTW>
; DI void inproj_tile(const Params& p, int l, int mt, int ntile, char* lds) {
;     ...
;   __syncthreads();
; #pragma unroll
;   for (int im = 0; im < 2; ++im) {
;     const int tl = wm * 64 + im * 32 + l31;
;     const float r = rn[(size_t)mt * 128 + tl];
	ds_read_b128 v[110:113], v64
	ds_read_b128 v[114:117], v67 offset:18432
	ds_read_b128 v[118:121], v64 offset:32
	ds_read_b128 v[122:125], v67 offset:18464
	v_mfma_f32_32x32x16_bf16 v[0:15], v[130:133], v[134:137], v[0:15]
	ds_read_b128 v[126:129], v64 offset:4608
	ds_read_b128 v[130:133], v64 offset:4640
	s_waitcnt lgkmcnt(4)
	v_mfma_f32_32x32x16_bf16 v[48:63], v[110:113], v[114:117], v[48:63]
	s_waitcnt lgkmcnt(1)
	v_mfma_f32_32x32x16_bf16 v[32:47], v[126:129], v[114:117], v[32:47]
	ds_read_b128 v[114:117], v67 offset:23040
	ds_read_b128 v[134:137], v67 offset:23072
	s_waitcnt lgkmcnt(1)
	v_mfma_f32_32x32x16_bf16 v[16:31], v[110:113], v[114:117], v[16:31]
	v_mfma_f32_32x32x16_bf16 v[0:15], v[126:129], v[114:117], v[0:15]
	v_mfma_f32_32x32x16_bf16 v[48:63], v[118:121], v[122:125], v[48:63]
	v_mfma_f32_32x32x16_bf16 v[32:47], v[130:133], v[122:125], v[32:47]
	s_waitcnt lgkmcnt(0)
	v_mfma_f32_32x32x16_bf16 v[16:31], v[118:121], v[134:137], v[16:31]
	ds_read_b128 v[110:113], v64 offset:64
	ds_read_b128 v[114:117], v67 offset:18496
	ds_read_b128 v[118:121], v64 offset:96
	ds_read_b128 v[122:125], v67 offset:18528
	v_mfma_f32_32x32x16_bf16 v[0:15], v[130:133], v[134:137], v[0:15]
	ds_read_b128 v[126:129], v64 offset:4672
	ds_read_b128 v[130:133], v64 offset:4704
	s_waitcnt lgkmcnt(4)
	v_mfma_f32_32x32x16_bf16 v[48:63], v[110:113], v[114:117], v[48:63]
	s_waitcnt lgkmcnt(1)
	v_mfma_f32_32x32x16_bf16 v[32:47], v[126:129], v[114:117], v[32:47]
	ds_read_b128 v[114:117], v67 offset:23104
	ds_read_b128 v[134:137], v67 offset:23136
	s_waitcnt lgkmcnt(1)
	v_mfma_f32_32x32x16_bf16 v[16:31], v[110:113], v[114:117], v[16:31]
	v_or_b32_e32 v110, 0x380, v178
	v_mov_b32_e32 v111, v179
	v_lshlrev_b64 v[154:155], 1, v[110:111]
	v_lshl_add_u64 v[110:111], s[0:1], 0, v[154:155]
	v_lshl_add_u64 v[150:151], s[4:5], 0, v[154:155]
	v_lshl_add_u64 v[152:153], s[6:7], 0, v[154:155]
	v_lshl_add_u64 v[156:157], s[8:9], 0, v[154:155]
	v_mfma_f32_32x32x16_bf16 v[0:15], v[126:129], v[114:117], v[0:15]
	v_lshl_add_u64 v[114:115], s[2:3], 0, v[154:155]
	v_lshl_add_u64 v[158:159], s[10:11], 0, v[154:155]
	global_load_dwordx4 v[110:113], v[110:111], off
	s_nop 0
	global_load_dwordx4 v[114:117], v[114:115], off
	v_or_b32_e32 v178, 0x3c0, v178
	v_mfma_f32_32x32x16_bf16 v[48:63], v[118:121], v[122:125], v[48:63]
	v_mfma_f32_32x32x16_bf16 v[32:47], v[130:133], v[122:125], v[32:47]
	global_load_dwordx4 v[122:125], v[72:73], off offset:1792
	global_load_dwordx4 v[126:129], v[84:85], off offset:1792
	s_waitcnt lgkmcnt(0)
	v_mfma_f32_32x32x16_bf16 v[16:31], v[118:121], v[134:137], v[16:31]
	global_load_dwordx4 v[118:121], v[150:151], off
	s_nop 0
	global_load_dwordx4 v[150:153], v[152:153], off
	s_nop 0
	global_load_dwordx4 v[154:157], v[156:157], off
	s_nop 0
	global_load_dwordx4 v[158:161], v[158:159], off
	s_waitcnt vmcnt(13)
	ds_write_b128 v66, v[102:105] offset:36864
	ds_write_b128 v68, v[90:93] offset:36864
	ds_write_b128 v70, v[94:97] offset:36864
	s_waitcnt vmcnt(11)
	ds_write_b128 v74, v[98:101] offset:36864
	ds_write_b128 v76, v[106:109] offset:36864
	s_waitcnt vmcnt(10)
	ds_write_b128 v78, v[138:141] offset:36864
	s_waitcnt vmcnt(9)
	ds_write_b128 v80, v[142:145] offset:36864
	s_waitcnt vmcnt(8)
	ds_write_b128 v82, v[146:149] offset:36864
	s_waitcnt lgkmcnt(0)
	s_barrier
	ds_read_b128 v[90:93], v64 offset:36864
	ds_read_b128 v[94:97], v67 offset:55296
	ds_read_b128 v[98:101], v64 offset:36896
	ds_read_b128 v[102:105], v67 offset:55328
	v_mfma_f32_32x32x16_bf16 v[0:15], v[130:133], v[134:137], v[0:15]
	ds_read_b128 v[106:109], v64 offset:41472
	ds_read_b128 v[130:133], v64 offset:41504
	v_lshlrev_b64 v[142:143], 1, v[178:179]
	v_lshl_add_u64 v[138:139], s[4:5], 0, v[142:143]
	s_waitcnt lgkmcnt(4)
	v_mfma_f32_32x32x16_bf16 v[48:63], v[90:93], v[94:97], v[48:63]
	s_waitcnt lgkmcnt(1)
	v_mfma_f32_32x32x16_bf16 v[32:47], v[106:109], v[94:97], v[32:47]
	ds_read_b128 v[94:97], v67 offset:59904
	ds_read_b128 v[134:137], v67 offset:59936
	s_waitcnt lgkmcnt(1)
	v_mfma_f32_32x32x16_bf16 v[16:31], v[90:93], v[94:97], v[16:31]
	v_mfma_f32_32x32x16_bf16 v[0:15], v[106:109], v[94:97], v[0:15]
	v_mfma_f32_32x32x16_bf16 v[48:63], v[98:101], v[102:105], v[48:63]
	v_mfma_f32_32x32x16_bf16 v[32:47], v[130:133], v[102:105], v[32:47]
	s_waitcnt lgkmcnt(0)
	v_mfma_f32_32x32x16_bf16 v[16:31], v[98:101], v[134:137], v[16:31]
	ds_read_b128 v[90:93], v64 offset:36928
	ds_read_b128 v[94:97], v67 offset:55360
	ds_read_b128 v[98:101], v64 offset:36960
	ds_read_b128 v[102:105], v67 offset:55392
	v_mfma_f32_32x32x16_bf16 v[0:15], v[130:133], v[134:137], v[0:15]
	ds_read_b128 v[106:109], v64 offset:41536
	ds_read_b128 v[130:133], v64 offset:41568
	s_waitcnt lgkmcnt(4)
	v_mfma_f32_32x32x16_bf16 v[48:63], v[90:93], v[94:97], v[48:63]
	s_waitcnt lgkmcnt(1)
	v_mfma_f32_32x32x16_bf16 v[32:47], v[106:109], v[94:97], v[32:47]
	ds_read_b128 v[94:97], v67 offset:59968
	ds_read_b128 v[134:137], v67 offset:60000
	s_waitcnt lgkmcnt(1)
	v_mfma_f32_32x32x16_bf16 v[16:31], v[90:93], v[94:97], v[16:31]
	v_lshl_add_u64 v[90:91], s[0:1], 0, v[142:143]
	s_add_u32 s0, s12, 0x4a40000
	s_addc_u32 s1, s13, 0
	v_mfma_f32_32x32x16_bf16 v[0:15], v[106:109], v[94:97], v[0:15]
	v_lshl_add_u64 v[94:95], s[2:3], 0, v[142:143]
	global_load_dwordx4 v[90:93], v[90:91], off
	s_nop 0
	global_load_dwordx4 v[94:97], v[94:95], off
	s_mov_b32 s2, 0
	v_mfma_f32_32x32x16_bf16 v[48:63], v[98:101], v[102:105], v[48:63]
	v_mfma_f32_32x32x16_bf16 v[32:47], v[130:133], v[102:105], v[32:47]
	global_load_dwordx4 v[102:105], v[72:73], off offset:1920
	global_load_dwordx4 v[106:109], v[84:85], off offset:1920
	v_lshl_add_u64 v[72:73], s[6:7], 0, v[142:143]
	v_lshl_add_u64 v[84:85], s[10:11], 0, v[142:143]
	s_waitcnt lgkmcnt(0)
	v_mfma_f32_32x32x16_bf16 v[16:31], v[98:101], v[134:137], v[16:31]
	global_load_dwordx4 v[98:101], v[138:139], off
	s_nop 0
	global_load_dwordx4 v[138:141], v[72:73], off
	v_lshl_add_u64 v[72:73], s[8:9], 0, v[142:143]
	global_load_dwordx4 v[142:145], v[72:73], off
	global_load_dwordx4 v[146:149], v[84:85], off
	s_waitcnt vmcnt(13)
	ds_write_b128 v66, v[122:125]
	ds_write_b128 v68, v[110:113]
	ds_write_b128 v70, v[114:117]
	s_waitcnt vmcnt(11)
	ds_write_b128 v74, v[118:121]
	ds_write_b128 v76, v[126:129]
	s_waitcnt vmcnt(10)
	ds_write_b128 v78, v[150:153]
	s_waitcnt vmcnt(9)
	ds_write_b128 v80, v[154:157]
	s_waitcnt vmcnt(8)
	ds_write_b128 v82, v[158:161]
	s_waitcnt lgkmcnt(0)
	s_barrier
; #define GLOAD(dst, kt_) _Pragma("unroll") for (int i = 0; i < NCH; ++i) { dst[i] = (i < NCHW) ? ldw(i, tid >> 3, (kt_) * 64 + (tid & 7) * 8) : ldx(i - NCHW, tid >> 3, (kt_) * 64 + (tid & 7) * 8); }
; #define LSTORE(src, base) _Pragma("unroll") for (int i = 0; i < NCH; ++i) { const int c = tid + 256 * i; *(u32x4*)((base) + (c >> 3) * 144 + (c & 7) * 16) = src[i]; }
; template <int WGN, int INS, int IMS, bool DB, class LdW, class LdX>
; DI void gemm_core(f32x16 (&acc)[INS][IMS], const int KT, LdW ldw, LdX ldx, char* lds, const int tid) {
;     ...
;     for (int kt = 0; kt < KT; kt += 2) {
;       if (kt + 2 < KT) { GLOAD(preA, kt + 2) }
;       COMPUTE_PIPE(lds)
;       LSTORE(preB, lds + BUFB)
;       __syncthreads();
;       if (kt + 3 < KT) { GLOAD(preB, kt + 3) }
;       COMPUTE_PIPE(lds + BUFB)
;       if (kt + 2 < KT) { LSTORE(preA, lds) }
;       __syncthreads();
;     }
	v_mfma_f32_32x32x16_bf16 v[0:15], v[130:133], v[134:137], v[0:15]
	ds_read_b128 v[110:113], v64
	ds_read_b128 v[114:117], v67 offset:18432
	ds_read_b128 v[118:121], v64 offset:32
	ds_read_b128 v[122:125], v67 offset:18464
	ds_read_b128 v[126:129], v64 offset:4608
	ds_read_b128 v[130:133], v64 offset:4640
	s_waitcnt lgkmcnt(4)
	v_mfma_f32_32x32x16_bf16 v[48:63], v[110:113], v[114:117], v[48:63]
	s_waitcnt lgkmcnt(1)
	v_mfma_f32_32x32x16_bf16 v[32:47], v[126:129], v[114:117], v[32:47]
	ds_read_b128 v[114:117], v67 offset:23040
	ds_read_b128 v[134:137], v67 offset:23072
	s_waitcnt lgkmcnt(1)
	v_mfma_f32_32x32x16_bf16 v[16:31], v[110:113], v[114:117], v[16:31]
	v_mfma_f32_32x32x16_bf16 v[0:15], v[126:129], v[114:117], v[0:15]
	v_mfma_f32_32x32x16_bf16 v[48:63], v[118:121], v[122:125], v[48:63]
	v_mfma_f32_32x32x16_bf16 v[32:47], v[130:133], v[122:125], v[32:47]
	s_waitcnt lgkmcnt(0)
	v_mfma_f32_32x32x16_bf16 v[16:31], v[118:121], v[134:137], v[16:31]
	ds_read_b128 v[110:113], v64 offset:64
	ds_read_b128 v[114:117], v67 offset:18496
	ds_read_b128 v[118:121], v64 offset:96
	ds_read_b128 v[122:125], v67 offset:18528
	v_mfma_f32_32x32x16_bf16 v[0:15], v[130:133], v[134:137], v[0:15]
	ds_read_b128 v[126:129], v64 offset:4672
	ds_read_b128 v[130:133], v64 offset:4704
	s_waitcnt lgkmcnt(4)
	v_mfma_f32_32x32x16_bf16 v[48:63], v[110:113], v[114:117], v[48:63]
	s_waitcnt lgkmcnt(1)
	v_mfma_f32_32x32x16_bf16 v[32:47], v[126:129], v[114:117], v[32:47]
	ds_read_b128 v[114:117], v67 offset:23104
	ds_read_b128 v[134:137], v67 offset:23136
	s_waitcnt vmcnt(5)
	ds_write_b128 v66, v[102:105] offset:36864
	ds_write_b128 v68, v[90:93] offset:36864
	ds_write_b128 v70, v[94:97] offset:36864
	s_waitcnt vmcnt(3)
	ds_write_b128 v74, v[98:101] offset:36864
	ds_write_b128 v76, v[106:109] offset:36864
	s_waitcnt vmcnt(2)
	ds_write_b128 v78, v[138:141] offset:36864
	s_waitcnt vmcnt(1)
	ds_write_b128 v80, v[142:145] offset:36864
	s_waitcnt vmcnt(0)
	ds_write_b128 v82, v[146:149] offset:36864
	s_waitcnt lgkmcnt(0)
	s_barrier
	ds_read_b128 v[68:71], v64 offset:36864
	ds_read_b128 v[72:75], v67 offset:55296
	ds_read_b128 v[76:79], v64 offset:36896
	ds_read_b128 v[80:83], v67 offset:55328
	v_mfma_f32_32x32x16_bf16 v[16:31], v[110:113], v[114:117], v[16:31]
	ds_read_b128 v[90:93], v64 offset:41472
	ds_read_b128 v[94:97], v64 offset:41504
	v_mfma_f32_32x32x16_bf16 v[0:15], v[126:129], v[114:117], v[0:15]
	v_mfma_f32_32x32x16_bf16 v[48:63], v[118:121], v[122:125], v[48:63]
	v_mfma_f32_32x32x16_bf16 v[32:47], v[130:133], v[122:125], v[32:47]
	v_mfma_f32_32x32x16_bf16 v[16:31], v[118:121], v[134:137], v[16:31]
	v_mfma_f32_32x32x16_bf16 v[0:15], v[130:133], v[134:137], v[0:15]
	s_waitcnt lgkmcnt(4)
	v_mfma_f32_32x32x16_bf16 v[48:63], v[68:71], v[72:75], v[48:63]
	s_waitcnt lgkmcnt(1)
	v_mfma_f32_32x32x16_bf16 v[32:47], v[90:93], v[72:75], v[32:47]
	ds_read_b128 v[72:75], v67 offset:59904
	ds_read_b128 v[98:101], v67 offset:59936
	s_waitcnt lgkmcnt(1)
	v_mfma_f32_32x32x16_bf16 v[16:31], v[68:71], v[72:75], v[16:31]
	ds_read_b128 v[68:71], v64 offset:36928
	ds_read_b128 v[102:105], v64 offset:36960
	ds_read_b128 v[106:109], v64 offset:41536
	ds_read_b128 v[110:113], v64 offset:41568
	v_or_b32_e32 v64, s80, v65
	v_lshlrev_b32_e32 v66, 2, v64
	v_mfma_f32_32x32x16_bf16 v[0:15], v[90:93], v[72:75], v[0:15]
	ds_read_b128 v[72:75], v67 offset:55360
	ds_read_b128 v[90:93], v67 offset:55392
	ds_read_b128 v[114:117], v67 offset:59968
	ds_read_b128 v[118:121], v67 offset:60000
	s_waitcnt lgkmcnt(0)
	s_barrier
	s_barrier
; template <int NTW>
; DI void inproj_tile(const Params& p, int l, int mt, int ntile, char* lds) {
;     ...
;   __syncthreads();
; #pragma unroll
;   for (int im = 0; im < 2; ++im) {
;     const int tl = wm * 64 + im * 32 + l31;
;     const float r = rn[(size_t)mt * 128 + tl];
; #pragma unroll
;     for (int in = 0; in < NTW; ++in)
; #pragma unroll
;       for (int g = 0; g < 4; ++g) {
;         const int n = wn * 32 * NTW + in * 32 + 8 * g + 4 * hi;
;         u32x2 o; o[0] = pk2(acc[in][im][4 * g] * r, acc[in][im][4 * g + 1] * r); o[1] = pk2(acc[in][im][4 * g + 2] * r, acc[in][im][4 * g + 3] * r);
;         *(u32x2*)(lds + tl * RS + n * 2) = o;
;       }
;   }
;   __syncthreads();
; #pragma unroll 4
;   for (int i = 0; i < NCOLS / 16; ++i) {
;     const int c = tid + 256 * i, tl = c / (NCOLS / 8), ch = c % (NCOLS / 8);
;     const u32x4 v = *(const u32x4*)(lds + tl * RS + ch * 16);
;     *(u32x4*)(proj + ((size_t)mt * 128 + tl) * NP + ntile * NCOLS + ch * 8) = v;
;   }
	global_load_dword v64, v66, s[0:1]
	v_or_b32_e32 v66, 0x80, v66
	global_load_dword v66, v66, s[0:1]
	v_mfma_f32_32x32x16_bf16 v[48:63], v[76:79], v[80:83], v[48:63]
	v_and_or_b32 v67, v87, 4, v88
	s_lshl_b32 s0, s14, 1
	s_add_u32 s0, s12, s0
	s_addc_u32 s1, s13, 0
	s_add_u32 s0, s0, 0x4a50000
	s_addc_u32 s1, s1, 0
	v_mfma_f32_32x32x16_bf16 v[32:47], v[94:97], v[80:83], v[32:47]
	v_mfma_f32_32x32x16_bf16 v[16:31], v[76:79], v[98:101], v[16:31]
	v_mfma_f32_32x32x16_bf16 v[0:15], v[94:97], v[98:101], v[0:15]
	v_mfma_f32_32x32x16_bf16 v[48:63], v[68:71], v[72:75], v[48:63]
	v_mfma_f32_32x32x16_bf16 v[32:47], v[106:109], v[72:75], v[32:47]
	v_mfma_f32_32x32x16_bf16 v[16:31], v[68:71], v[114:117], v[16:31]
	v_mfma_f32_32x32x16_bf16 v[0:15], v[106:109], v[114:117], v[0:15]
	v_mfma_f32_32x32x16_bf16 v[48:63], v[102:105], v[90:93], v[48:63]
	v_mfma_f32_32x32x16_bf16 v[32:47], v[110:113], v[90:93], v[32:47]
	s_waitcnt vmcnt(1)
	s_nop 9
	v_mul_f32_e64 v48, v48, v64
	v_mul_f32_e64 v49, v49, v64
	v_mul_f32_e64 v50, v50, v64
	v_mul_f32_e64 v51, v51, v64
	v_cvt_pk_bf16_f32 v48, v48, v49
	v_mfma_f32_32x32x16_bf16 v[16:31], v[102:105], v[118:121], v[16:31]
	v_cvt_pk_bf16_f32 v49, v50, v51
	v_lshlrev_b32_e32 v50, 1, v67
	v_mad_u32_u24 v65, v65, s75, v50
	v_mul_f32_e64 v32, v32, v64
	v_mul_f32_e64 v33, v33, v64
	v_pk_mul_f32 v[34:35], v[34:35], v[64:65] op_sel_hi:[1,0]
	v_pk_mul_f32 v[50:51], v[52:53], v[64:65] op_sel_hi:[1,0]
	v_pk_mul_f32 v[52:53], v[54:55], v[64:65] op_sel_hi:[1,0]
	v_mfma_f32_32x32x16_bf16 v[0:15], v[110:113], v[118:121], v[0:15]
	s_waitcnt vmcnt(0)
	s_nop 1
	v_mul_f32_e64 v16, v16, v66
	v_mul_f32_e64 v17, v17, v66
	v_mul_f32_e64 v18, v18, v66
	v_mul_f32_e64 v19, v19, v66
	v_cvt_pk_bf16_f32 v32, v32, v33
	v_cvt_pk_bf16_f32 v33, v34, v35
	v_pk_mul_f32 v[34:35], v[36:37], v[64:65] op_sel_hi:[1,0]
	v_pk_mul_f32 v[36:37], v[38:39], v[64:65] op_sel_hi:[1,0]
	v_cvt_pk_bf16_f32 v16, v16, v17
	v_pk_mul_f32 v[0:1], v[0:1], v[66:67] op_sel_hi:[1,0]
	v_pk_mul_f32 v[2:3], v[2:3], v[66:67] op_sel_hi:[1,0]
	v_cvt_pk_bf16_f32 v17, v18, v19
	v_pk_mul_f32 v[18:19], v[20:21], v[66:67] op_sel_hi:[1,0]
	v_pk_mul_f32 v[20:21], v[22:23], v[66:67] op_sel_hi:[1,0]
	v_cvt_pk_bf16_f32 v0, v0, v1
	v_cvt_pk_bf16_f32 v1, v2, v3
	v_pk_mul_f32 v[2:3], v[4:5], v[66:67] op_sel_hi:[1,0]
	v_pk_mul_f32 v[4:5], v[6:7], v[66:67] op_sel_hi:[1,0]
	v_cvt_pk_bf16_f32 v50, v50, v51
	v_cvt_pk_bf16_f32 v51, v52, v53
	v_cvt_pk_bf16_f32 v34, v34, v35
	v_cvt_pk_bf16_f32 v35, v36, v37
	v_cvt_pk_bf16_f32 v18, v18, v19
	v_cvt_pk_bf16_f32 v19, v20, v21
	v_add_u32_e32 v22, 0x2000, v65
	v_cvt_pk_bf16_f32 v2, v2, v3
	v_cvt_pk_bf16_f32 v3, v4, v5
	ds_write2_b64 v65, v[48:49], v[50:51] offset1:2
	v_pk_mul_f32 v[48:49], v[56:57], v[64:65] op_sel_hi:[1,0]
	v_pk_mul_f32 v[50:51], v[58:59], v[64:65] op_sel_hi:[1,0]
	ds_write2_b64 v65, v[32:33], v[34:35] offset0:8 offset1:10
	v_pk_mul_f32 v[32:33], v[40:41], v[64:65] op_sel_hi:[1,0]
	v_pk_mul_f32 v[34:35], v[42:43], v[64:65] op_sel_hi:[1,0]
	ds_write2_b64 v22, v[16:17], v[18:19] offset0:64 offset1:66
	v_pk_mul_f32 v[16:17], v[24:25], v[66:67] op_sel_hi:[1,0]
	v_pk_mul_f32 v[18:19], v[26:27], v[66:67] op_sel_hi:[1,0]
	ds_write2_b64 v22, v[0:1], v[2:3] offset0:72 offset1:74
	v_pk_mul_f32 v[0:1], v[8:9], v[66:67] op_sel_hi:[1,0]
	v_pk_mul_f32 v[2:3], v[10:11], v[66:67] op_sel_hi:[1,0]
	v_cvt_pk_bf16_f32 v48, v48, v49
	v_cvt_pk_bf16_f32 v49, v50, v51
	v_pk_mul_f32 v[50:51], v[60:61], v[64:65] op_sel_hi:[1,0]
	v_pk_mul_f32 v[52:53], v[62:63], v[64:65] op_sel_hi:[1,0]
	v_cvt_pk_bf16_f32 v32, v32, v33
	v_cvt_pk_bf16_f32 v33, v34, v35
	v_pk_mul_f32 v[34:35], v[44:45], v[64:65] op_sel_hi:[1,0]
	v_pk_mul_f32 v[36:37], v[46:47], v[64:65] op_sel_hi:[1,0]
	v_cvt_pk_bf16_f32 v16, v16, v17
	v_cvt_pk_bf16_f32 v17, v18, v19
	v_pk_mul_f32 v[18:19], v[28:29], v[66:67] op_sel_hi:[1,0]
	v_pk_mul_f32 v[20:21], v[30:31], v[66:67] op_sel_hi:[1,0]
	v_cvt_pk_bf16_f32 v0, v0, v1
	v_cvt_pk_bf16_f32 v1, v2, v3
	v_pk_mul_f32 v[2:3], v[12:13], v[66:67] op_sel_hi:[1,0]
	v_pk_mul_f32 v[4:5], v[14:15], v[66:67] op_sel_hi:[1,0]
	v_cvt_pk_bf16_f32 v50, v50, v51
	v_cvt_pk_bf16_f32 v51, v52, v53
	v_cvt_pk_bf16_f32 v34, v34, v35
	v_cvt_pk_bf16_f32 v35, v36, v37
	v_cvt_pk_bf16_f32 v18, v18, v19
	v_cvt_pk_bf16_f32 v19, v20, v21
	v_cvt_pk_bf16_f32 v2, v2, v3
	v_cvt_pk_bf16_f32 v3, v4, v5
	ds_write2_b64 v65, v[48:49], v[50:51] offset0:4 offset1:6
	ds_write2_b64 v65, v[32:33], v[34:35] offset0:12 offset1:14
	ds_write2_b64 v22, v[16:17], v[18:19] offset0:68 offset1:70
	ds_write2_b64 v22, v[0:1], v[2:3] offset0:76 offset1:78
	s_waitcnt lgkmcnt(0)
	s_barrier
.LBB0_224:
	v_lshrrev_b32_e32 v4, 4, v86
	v_and_b32_e32 v5, 15, v86
	v_lshlrev_b32_e32 v5, 4, v5
	v_mad_u32_u24 v6, v4, s75, v5
	v_mad_u32_u24 v7, v4, s33, v5
	s_mul_i32 s4, s80, s33
	s_add_u32 s4, s0, s4
	s_addc_u32 s5, s1, 0
	ds_read_b128 v[12:15], v6
	ds_read_b128 v[16:19], v6 offset:4352
	ds_read_b128 v[20:23], v6 offset:8704
	ds_read_b128 v[24:27], v6 offset:13056
	ds_read_b128 v[28:31], v6 offset:17408
	ds_read_b128 v[32:35], v6 offset:21760
	ds_read_b128 v[36:39], v6 offset:26112
	ds_read_b128 v[40:43], v6 offset:30464
	s_waitcnt lgkmcnt(7)
	global_store_dwordx4 v7, v[12:15], s[4:5]
	s_add_u32 s4, s4, 0x1a000
	s_addc_u32 s5, s5, 0
	s_waitcnt lgkmcnt(6)
	global_store_dwordx4 v7, v[16:19], s[4:5]
	s_add_u32 s4, s4, 0x1a000
	s_addc_u32 s5, s5, 0
	s_waitcnt lgkmcnt(5)
	global_store_dwordx4 v7, v[20:23], s[4:5]
	s_add_u32 s4, s4, 0x1a000
	s_addc_u32 s5, s5, 0
	s_waitcnt lgkmcnt(4)
	global_store_dwordx4 v7, v[24:27], s[4:5]
	s_add_u32 s4, s4, 0x1a000
	s_addc_u32 s5, s5, 0
	s_waitcnt lgkmcnt(3)
	global_store_dwordx4 v7, v[28:31], s[4:5]
	s_add_u32 s4, s4, 0x1a000
	s_addc_u32 s5, s5, 0
	s_waitcnt lgkmcnt(2)
	global_store_dwordx4 v7, v[32:35], s[4:5]
	s_add_u32 s4, s4, 0x1a000
	s_addc_u32 s5, s5, 0
	s_waitcnt lgkmcnt(1)
	global_store_dwordx4 v7, v[36:39], s[4:5]
	s_add_u32 s4, s4, 0x1a000
	s_addc_u32 s5, s5, 0
	s_waitcnt lgkmcnt(0)
	global_store_dwordx4 v7, v[40:43], s[4:5]
	s_setprio 0
